# comb1 + gMLP V-row loads pipelined one group earlier + gMLP/conv unit order grouped by XCD
# speedup vs baseline: 1.0011x; 1.0011x over previous
; __device__ __forceinline__ int opaque0() { int z; asm volatile("s_mov_b32 %0, 0" : "=s"(z)); return z; }
; #define KIN(i) (*(const float* const __attribute__((address_space(4)))*)(kp + kz + 8 * (i)))
; __global__ void __launch_bounds__(NTHR, 2) fwd_megakernel(Args args) {
;     ...
;     if (IN(4)) { const int kz = opaque0();
;         for (int cu = bid; cu < T / 32; cu += G) {
;             const int t0 = cu * 32, tb = (t0 / SEQ) * SEQ;
;             f32x2 wk[31];
; #pragma unroll
;             for (int k = 0; k < 31; ++k) wk[k] = *(const f32x2*)(KIN(I_CONV_W) + k * CCH + 2 * tid);
;             const f32x2 cb = *(const f32x2*)(KIN(I_CONV_B) + 2 * tid);
.LBB0_559:
	s_cmp_lt_i32 s16, 5
	s_cselect_b64 s[40:41], -1, 0
	s_add_u32 s6, s14, 0x15500000
	s_addc_u32 s7, s15, 0
	s_and_b64 s[2:3], s[40:41], s[2:3]
	s_andn2_b64 vcc, exec, s[2:3]
	s_cbranch_vccnz .LBB0_775
	s_cmpk_gt_i32 s10, 0xff
	s_mov_b32 s42, 0
	s_cbranch_scc1 .LBB0_775
	s_ashr_i32 s43, s42, 31
	s_add_u32 s2, s0, s42
	s_addc_u32 s3, s1, s43
	s_load_dwordx8 s[20:27], s[2:3], 0x38
	v_lshlrev_b32_e32 v0, 3, v221
	s_load_dwordx2 s[2:3], s[2:3], 0x78
	s_waitcnt lgkmcnt(0)
	v_mov_b32_e32 v1, 0
	v_add_u32_e32 v218, 0, v0
	v_lshl_add_u64 v[20:21], s[20:21], 0, v[0:1]
	v_lshl_add_u64 v[22:23], s[22:23], 0, v[0:1]
	v_lshlrev_b32_e32 v0, 4, v220
	v_lshl_add_u64 v[30:31], s[2:3], 0, v[0:1]
	s_mov_b64 s[2:3], 0x1000
	v_lshl_add_u64 v[34:35], v[20:21], 0, s[2:3]
	s_mov_b64 s[2:3], 0x2000
	v_lshl_add_u64 v[36:37], v[20:21], 0, s[2:3]
	s_mov_b64 s[2:3], 0x3000
	v_lshl_add_u64 v[38:39], v[20:21], 0, s[2:3]
	s_mov_b64 s[2:3], 0x4000
	v_lshl_add_u64 v[40:41], v[20:21], 0, s[2:3]
	s_mov_b64 s[2:3], 0x5000
	v_lshl_add_u64 v[42:43], v[20:21], 0, s[2:3]
	s_mov_b64 s[2:3], 0x6000
	v_lshl_add_u64 v[44:45], v[20:21], 0, s[2:3]
	s_mov_b64 s[2:3], 0x7000
	v_lshl_add_u64 v[46:47], v[20:21], 0, s[2:3]
	s_mov_b64 s[2:3], 0x8000
	v_lshlrev_b32_e32 v2, 2, v221
	v_mov_b32_e32 v3, v1
	v_lshl_add_u64 v[48:49], v[20:21], 0, s[2:3]
	s_mov_b64 s[2:3], 0x9000
	v_lshl_add_u64 v[24:25], s[28:29], 0, v[2:3]
	v_mbcnt_lo_u32_b32 v2, -1, 0
	v_lshl_add_u64 v[50:51], v[20:21], 0, s[2:3]
	s_mov_b64 s[2:3], 0xa000
	v_mbcnt_hi_u32_b32 v2, -1, v2
	s_waitcnt vmcnt(0)
	v_lshl_add_u64 v[52:53], v[20:21], 0, s[2:3]
	s_mov_b64 s[2:3], 0xb000
	v_and_b32_e32 v3, 64, v2
	v_lshl_add_u64 v[54:55], v[20:21], 0, s[2:3]
	s_mov_b64 s[2:3], 0xc000
	v_add_u32_e32 v3, 64, v3
	v_xor_b32_e32 v4, 1, v2
	v_lshl_add_u64 v[56:57], v[20:21], 0, s[2:3]
	s_mov_b64 s[2:3], 0xd000
	v_cmp_lt_i32_e32 vcc, v4, v3
	v_lshl_add_u64 v[58:59], v[20:21], 0, s[2:3]
	s_mov_b64 s[2:3], 0xe000
	v_cndmask_b32_e32 v4, v2, v4, vcc
	v_lshl_add_u64 v[60:61], v[20:21], 0, s[2:3]
	s_mov_b64 s[2:3], 0xf000
	v_lshlrev_b32_e32 v222, 2, v4
	v_xor_b32_e32 v4, 2, v2
	v_lshl_add_u64 v[62:63], v[20:21], 0, s[2:3]
	s_mov_b64 s[2:3], 0x10000
	v_cmp_lt_i32_e32 vcc, v4, v3
	v_lshl_add_u64 v[64:65], v[20:21], 0, s[2:3]
	s_mov_b64 s[2:3], 0x11000
	v_cndmask_b32_e32 v4, v2, v4, vcc
	v_lshl_add_u64 v[66:67], v[20:21], 0, s[2:3]
	s_mov_b64 s[2:3], 0x12000
	v_lshlrev_b32_e32 v223, 2, v4
	v_xor_b32_e32 v4, 4, v2
	v_lshl_add_u64 v[68:69], v[20:21], 0, s[2:3]
	s_mov_b64 s[2:3], 0x13000
	v_cmp_lt_i32_e32 vcc, v4, v3
	v_lshl_add_u64 v[70:71], v[20:21], 0, s[2:3]
	s_mov_b64 s[2:3], 0x14000
	v_cndmask_b32_e32 v4, v2, v4, vcc
	v_lshl_add_u64 v[72:73], v[20:21], 0, s[2:3]
	s_mov_b64 s[2:3], 0x15000
	v_lshlrev_b32_e32 v224, 2, v4
	v_xor_b32_e32 v4, 8, v2
	v_lshl_add_u64 v[74:75], v[20:21], 0, s[2:3]
	s_mov_b64 s[2:3], 0x16000
	v_cmp_lt_i32_e32 vcc, v4, v3
	v_lshl_add_u64 v[76:77], v[20:21], 0, s[2:3]
	s_mov_b64 s[2:3], 0x17000
	v_cndmask_b32_e32 v4, v2, v4, vcc
	v_lshl_add_u64 v[78:79], v[20:21], 0, s[2:3]
	s_mov_b64 s[2:3], 0x18000
	v_lshlrev_b32_e32 v225, 2, v4
	v_xor_b32_e32 v4, 16, v2
	v_lshl_add_u64 v[80:81], v[20:21], 0, s[2:3]
	s_mov_b64 s[2:3], 0x19000
	v_cmp_lt_i32_e32 vcc, v4, v3
	v_lshl_add_u64 v[82:83], v[20:21], 0, s[2:3]
	s_mov_b64 s[2:3], 0x1a000
	v_cndmask_b32_e32 v4, v2, v4, vcc
	v_lshl_add_u64 v[84:85], v[20:21], 0, s[2:3]
	s_mov_b64 s[2:3], 0x1b000
	v_lshlrev_b32_e32 v216, 2, v4
	v_xor_b32_e32 v4, 32, v2
	v_lshl_add_u64 v[86:87], v[20:21], 0, s[2:3]
	s_mov_b64 s[2:3], 0x1c000
	s_lshl_b32 s56, s95, 2
	v_cmp_lt_i32_e32 vcc, v4, v3
	v_lshl_add_u64 v[88:89], v[20:21], 0, s[2:3]
	s_mov_b64 s[2:3], 0x1d000
	v_add_u32_e32 v219, 0, v0
	v_cndmask_b32_e32 v2, v2, v4, vcc
	v_lshl_add_u64 v[26:27], s[24:25], 0, v[0:1]
	v_lshl_add_u64 v[28:29], s[26:27], 0, v[0:1]
	v_lshlrev_b32_e32 v0, 3, v220
	v_lshl_add_u64 v[90:91], v[20:21], 0, s[2:3]
	s_mov_b64 s[2:3], 0x1e000
	s_or_b32 s25, s56, 1
	s_or_b32 s27, s56, 2
	s_or_b32 s58, s56, 3
	v_lshlrev_b32_e32 v217, 2, v2
	v_lshl_add_u64 v[32:33], s[6:7], 0, v[0:1]
	v_lshl_add_u64 v[92:93], v[20:21], 0, s[2:3]
	s_lshl_b32 s24, s95, 14
	s_lshl_b32 s26, s25, 12
	s_lshl_b32 s57, s27, 12
	s_lshl_b32 s59, s58, 12
	v_mov_b32_e32 v226, 0x3727c5ac
	s_mov_b32 s60, 0x800000
	v_mov_b32_e32 v227, 0x358637bd
	s_and_b32 s61, s10, 7
	s_lshl_b32 s61, s61, 5
	s_lshr_b32 s2, s10, 3
	s_or_b32 s61, s61, s2
	s_branch .LBB0_563

; #define LAS __attribute__((address_space(3)))
; #define KIN(i) (*(const float* const __attribute__((address_space(4)))*)(kp + kz + 8 * (i)))
; __global__ void __launch_bounds__(NTHR, 2) fwd_megakernel(Args args) {
;     ...
;         for (int su = bid; su < T / 32; su += G) {
;             const int tc0 = (su >> 2) * 128, qi = su & 3, i0 = 32 * qi, J = qi < 2 ? 64 : 128;
;             constexpr int LDB = 136;
;             LAS bf16_t* Bt = (LAS bf16_t*)lds;
;             LAS f32x2* st = (LAS f32x2*)(lds + 2 * 128 * LDB * 2);
;             LAS float* red = (LAS float*)(lds + 2 * 128 * LDB * 2 + 1024);
;             if (tid < J) { const f32x4* p = (const f32x4*)(VSTAT + (size_t)(tc0 + tid) * 32); float s1 = 0.f, s2 = 0.f;
; #pragma unroll
;                 for (int j = 0; j < 8; ++j) { const f32x4 v = p[j]; s1 += v[0] + v[2]; s2 += v[1] + v[3]; }
;                 const float mean = s1 * (1.0f / CCH), var = fmaxf(s2 * (1.0f / CCH) - mean * mean, 0.f); st[tid] = (f32x2){mean, rsqrtf(var + LN_EPS)}; }
;             const int mb = wave & 1, nq = wave >> 1, fr = lane & 15, fq = lane >> 4;
;             const int trow = tc0 + i0 + 16 * mb + fr;
;             const float* lng = KIN(I_SGU_LN_G); const float* lnb = KIN(I_SGU_LN_B); const float* sgb = KIN(I_SGU_B);
;             const int c8 = tid & 15, jb = tid >> 4, nk = J / 32;
;             u32x4 pv[4]; f32x4 pg0, pg1, pb0, pb1; bf16x8 pw[4]; u32x2 pu0, pu1; float pbs;
.LBB0_657:
	v_readlane_b32 s2, v254, 3
	s_add_i32 s11, 0, 0x11000
	s_bfe_u32 s4, s2, 0x10006
	s_lshr_b32 s5, s2, 7
	v_and_b32_e32 v2, 15, v221
	s_add_u32 s2, s0, s42
	v_mov_b32_e32 v121, 0
	v_lshl_or_b32 v155, s4, 4, v2
	s_addc_u32 s3, s1, s43
	v_and_b32_e32 v0, 48, v220
	v_mov_b32_e32 v1, v121
	s_lshl_b32 s4, s4, 8
	s_load_dwordx4 s[24:27], s[2:3], 0x58
	s_load_dwordx2 s[20:21], s[2:3], 0x70
	v_lshl_add_u64 v[0:1], s[14:15], 0, v[0:1]
	s_mov_b64 s[2:3], 0xbc00000
	s_add_i32 s4, s4, 0
	v_lshl_add_u64 v[128:129], v[0:1], 0, s[2:3]
	s_lshl_b32 s18, s5, 5
	v_mov_b32_e32 v0, 0x68
	s_add_i32 s4, s4, 0x11400
	s_lshl_b32 s5, s5, 6
	v_lshlrev_b32_e32 v120, 4, v2
	v_bitop3_b32 v7, s18, v0, v2 bitop3:0xc8
	s_add_i32 s23, s4, s5
	v_lshlrev_b32_e32 v0, 2, v2
	v_lshrrev_b32_e32 v3, 4, v220
	v_lshl_add_u64 v[122:123], s[36:37], 0, v[120:121]
	v_lshlrev_b32_e32 v120, 5, v2
	v_add_u32_e32 v175, s4, v0
	s_add_u32 s4, s88, s5
	s_waitcnt lgkmcnt(0)
	v_lshl_add_u64 v[124:125], s[24:25], 0, v[120:121]
	v_lshl_add_u64 v[126:127], s[26:27], 0, v[120:121]
	v_lshlrev_b32_e32 v120, 3, v3
	s_addc_u32 s5, s89, 0
	v_lshrrev_b32_e32 v163, 4, v221
	v_lshlrev_b32_e32 v4, 3, v2
	v_lshl_add_u64 v[130:131], s[4:5], 0, v[120:121]
	s_movk_i32 s4, 0x880
	v_or_b32_e32 v1, s18, v2
	v_add_u32_e32 v169, s23, v0
	v_lshl_or_b32 v0, v3, 2, s18
	v_mad_u32_u24 v2, v2, s4, 0
	v_xor_b32_e32 v3, v163, v4
	v_lshl_add_u32 v186, v3, 1, v2
	v_add_u32_e32 v3, 32, v163
	v_lshl_add_u32 v187, v3, 3, s11
	v_xor_b32_e32 v3, v3, v4
	v_lshl_add_u32 v188, v3, 1, v2
	v_or_b32_e32 v3, 64, v163
	v_lshl_add_u32 v189, v3, 3, s11
	v_bitop3_b32 v3, v163, v4, 64 bitop3:0x36
	s_movk_i32 s2, 0x110
	v_lshl_add_u32 v190, v3, 1, v2
	v_add_u32_e32 v3, 0x60, v163
	v_mul_lo_u32 v6, v1, s2
	s_movk_i32 s19, 0x68
	s_movk_i32 s22, 0x78
	v_lshl_add_u32 v191, v3, 3, s11
	v_xor_b32_e32 v3, v3, v4
	v_or_b32_e32 v5, 16, v1
	v_bitop3_b32 v8, v1, s22, 16 bitop3:0xc8
	v_lshl_add_u32 v192, v3, 1, v2
	v_add_u32_e32 v2, 0, v6
	v_bitop3_b32 v1, v120, v1, s19 bitop3:0x78
	v_add_u32_e32 v3, 0x1100, v2
	v_lshl_add_u32 v193, v1, 1, v2
	v_bitop3_b32 v1, v120, v5, s22 bitop3:0x78
	v_lshl_add_u32 v194, v1, 1, v3
	v_bitop3_b32 v1, v120, v7, 32 bitop3:0x36
	v_lshl_add_u32 v195, v1, 1, v2
	v_bitop3_b32 v1, v120, v8, 32 bitop3:0x36
	v_lshl_add_u32 v196, v1, 1, v3
	v_bitop3_b32 v1, v120, v7, 64 bitop3:0x36
	s_movk_i32 s4, 0x60
	v_lshl_add_u32 v197, v1, 1, v2
	v_bitop3_b32 v1, v120, v8, 64 bitop3:0x36
	v_lshl_add_u32 v198, v1, 1, v3
	v_bitop3_b32 v1, v120, v7, s4 bitop3:0x36
	v_lshl_add_u32 v199, v1, 1, v2
	v_bitop3_b32 v1, v120, v8, s4 bitop3:0x36
	v_lshlrev_b32_e32 v120, 1, v0
	v_lshl_add_u32 v137, v221, 3, s11
	v_cmp_gt_u32_e64 s[2:3], 16, v220
	v_lshl_add_u32 v181, v163, 3, s11
	v_lshl_add_u32 v200, v1, 1, v3
	v_lshl_add_u64 v[132:133], s[6:7], 0, v[120:121]
	s_lshl_b32 s23, s10, 5
	s_lshl_b32 s56, s34, 5
	s_mov_b32 s22, 0x3a800000
	s_mov_b32 s57, 0x800000
	s_mov_b64 s[24:25], 0x10000
	v_mov_b32_e32 v201, 0x358637bd
	v_lshlrev_b32_e32 v202, 2, v0
	s_lshr_b32 s4, s10, 5
	s_lshl_b32 s4, s4, 3
	s_and_b32 s5, s10, 7
	s_add_i32 s4, s4, s5
	s_lshl_b32 s4, s4, 2
	s_bfe_u32 s5, s10, 0x20003
	s_or_b32 s58, s4, s5
	s_lshl_b32 s23, s58, 5
	s_branch .LBB0_659

.LBB0_669:
	v_or_b32_e32 v134, s11, v48
	v_ashrrev_i32_e32 v135, 31, v134
	v_lshlrev_b32_e32 v120, 2, v48
	v_lshlrev_b64 v[48:49], 11, v[134:135]
	v_lshl_add_u64 v[150:151], v[130:131], 0, v[48:49]
	global_load_dword v136, v120, s[20:21]
	global_load_dwordx2 v[140:141], v[150:151], off
	global_load_dwordx2 v[138:139], v[150:151], off offset:32
	s_mov_b64 s[100:101], vcc
	v_lshl_add_u64 v[226:227], v[112:113], 0, s[24:25]
	global_load_dwordx4 v[222:225], v[112:113], off offset:256
	global_load_dwordx4 v[226:229], v[226:227], off offset:256
	s_mov_b64 vcc, s[4:5]
	s_cbranch_vccnz .Lgpv_g1
	v_lshlrev_b64 v[230:231], 11, v[152:153]
	v_lshl_add_u64 v[230:231], v[122:123], 0, v[230:231]
	v_lshl_add_u64 v[234:235], v[230:231], 0, s[24:25]
	global_load_dwordx4 v[230:233], v[230:231], off offset:256
	global_load_dwordx4 v[234:237], v[234:235], off offset:256
; #define LAS __attribute__((address_space(3)))
; __device__ __forceinline__ unsigned cvt_pk_bf16(float lo, float hi) { unsigned r; asm volatile("v_cvt_pk_bf16_f32 %0, %1, %2" : "=v"(r) : "v"(lo), "v"(hi)); return r; }
; __device__ __forceinline__ float bf_lo(unsigned u) { return __uint_as_float(u << 16); }
; __device__ __forceinline__ float bf_hi(unsigned u) { return __uint_as_float(u & 0xffff0000u); }
; __global__ void __launch_bounds__(NTHR, 2) fwd_megakernel(Args args) {
;     ...
;             for (int h = 0; h < 8; ++h) {
;                 LAS bf16_t* Bc = Bt + (h & 1) * (128 * LDB);
; #pragma unroll
;                 for (int k = 0; k < 4; ++k) if (k < nk) { const int j = jb + 32 * k; const u32x4 v = pv[k]; const f32x2 ms = st[j];
;                     const f32x4 x0 = (f32x4){bf_lo(v.x), bf_hi(v.x), bf_lo(v.y), bf_hi(v.y)}, x1 = (f32x4){bf_lo(v.z), bf_hi(v.z), bf_lo(v.w), bf_hi(v.w)};
;                     const f32x4 y0 = (x0 - ms.x) * ms.y * pg0 + pb0, y1 = (x1 - ms.x) * ms.y * pg1 + pb1;
;                     LAS bf16_t* d = Bc + (c8 * 8) * LDB + (j ^ (8 * c8));
;                     const unsigned p0 = cvt_pk_bf16(y0[0], y0[1]), p1 = cvt_pk_bf16(y0[2], y0[3]), p2 = cvt_pk_bf16(y1[0], y1[1]), p3 = cvt_pk_bf16(y1[2], y1[3]);
;                     d[0 * LDB] = (bf16_t)(p0 & 0xffffu); d[1 * LDB] = (bf16_t)(p0 >> 16); d[2 * LDB] = (bf16_t)(p1 & 0xffffu); d[3 * LDB] = (bf16_t)(p1 >> 16);
;                     d[4 * LDB] = (bf16_t)(p2 & 0xffffu); d[5 * LDB] = (bf16_t)(p2 >> 16); d[6 * LDB] = (bf16_t)(p3 & 0xffffu); d[7 * LDB] = (bf16_t)(p3 >> 16); }
;                 bf16x8 cw[4];
; #pragma unroll
;                 for (int ks = 0; ks < 4; ++ks) cw[ks] = pw[ks];
;                 const u32x2 u0 = pu0, u1 = pu1; const float bs = pbs;
;                 __syncthreads();
;                 if (h + 1 < 8) SGU_PREFETCH(h + 1);
.Lgpv_g1:
	s_mov_b64 vcc, s[100:101]
	s_waitcnt lgkmcnt(0)
	s_barrier
	ds_read_b64 v[48:49], v181
	s_waitcnt vmcnt(12)
	v_lshlrev_b32_e32 v50, 16, v44
	v_and_b32_e32 v51, 0xffff0000, v44
	v_lshlrev_b32_e32 v44, 16, v45
	v_and_b32_e32 v45, 0xffff0000, v45
	v_lshlrev_b32_e32 v52, 16, v46
	v_and_b32_e32 v53, 0xffff0000, v46
	v_lshlrev_b32_e32 v54, 16, v47
	v_and_b32_e32 v55, 0xffff0000, v47
	s_waitcnt lgkmcnt(0)
	v_sub_f32_e32 v47, v51, v48
	v_sub_f32_e32 v46, v50, v48
	v_sub_f32_e32 v45, v45, v48
	v_sub_f32_e32 v44, v44, v48
	v_pk_mul_f32 v[46:47], v[48:49], v[46:47] op_sel:[1,0]
	v_pk_mul_f32 v[44:45], v[48:49], v[44:45] op_sel:[1,0]
	s_waitcnt vmcnt(7)
	v_pk_fma_f32 v[46:47], v[24:25], v[46:47], v[28:29]
	v_sub_f32_e32 v51, v55, v48
	v_sub_f32_e32 v50, v54, v48
	v_sub_f32_e32 v53, v53, v48
	v_sub_f32_e32 v52, v52, v48
	v_pk_fma_f32 v[44:45], v[26:27], v[44:45], v[30:31]
	v_pk_mul_f32 v[52:53], v[48:49], v[52:53] op_sel:[1,0]
	v_pk_mul_f32 v[48:49], v[48:49], v[50:51] op_sel:[1,0]
	v_cvt_pk_bf16_f32 v46, v46, v47
	v_pk_fma_f32 v[50:51], v[16:17], v[52:53], v[20:21]
	v_pk_fma_f32 v[48:49], v[18:19], v[48:49], v[22:23]
	v_cvt_pk_bf16_f32 v44, v44, v45
	v_cvt_pk_bf16_f32 v45, v50, v51
	v_lshlrev_b32_e32 v50, 16, v43
	v_cvt_pk_bf16_f32 v47, v48, v49
	ds_write_b16 v186, v46
	ds_write_b16_d16_hi v186, v46 offset:272
	ds_write_b16 v186, v44 offset:544
	ds_write_b16_d16_hi v186, v44 offset:816
	ds_write_b16 v186, v45 offset:1088
	ds_write_b16_d16_hi v186, v45 offset:1360
	ds_write_b16 v186, v47 offset:1632
	ds_write_b16_d16_hi v186, v47 offset:1904
	ds_read_b64 v[44:45], v187
	v_lshlrev_b32_e32 v46, 16, v40
	v_and_b32_e32 v47, 0xffff0000, v40
	v_lshlrev_b32_e32 v40, 16, v41
	v_and_b32_e32 v41, 0xffff0000, v41
	v_lshlrev_b32_e32 v48, 16, v42
	v_and_b32_e32 v49, 0xffff0000, v42
	v_and_b32_e32 v51, 0xffff0000, v43
	s_waitcnt lgkmcnt(0)
	v_sub_f32_e32 v43, v47, v44
	v_sub_f32_e32 v42, v46, v44
	v_sub_f32_e32 v41, v41, v44
	v_sub_f32_e32 v40, v40, v44
	v_pk_mul_f32 v[42:43], v[44:45], v[42:43] op_sel:[1,0]
	v_pk_mul_f32 v[40:41], v[44:45], v[40:41] op_sel:[1,0]
	v_pk_fma_f32 v[42:43], v[24:25], v[42:43], v[28:29]
	v_sub_f32_e32 v47, v51, v44
	v_sub_f32_e32 v46, v50, v44
	v_sub_f32_e32 v49, v49, v44
	v_sub_f32_e32 v48, v48, v44
	v_pk_fma_f32 v[40:41], v[26:27], v[40:41], v[30:31]
	v_pk_mul_f32 v[48:49], v[44:45], v[48:49] op_sel:[1,0]
	v_pk_mul_f32 v[44:45], v[44:45], v[46:47] op_sel:[1,0]
	v_cvt_pk_bf16_f32 v42, v42, v43
	s_and_b64 vcc, exec, s[4:5]
	v_pk_fma_f32 v[44:45], v[18:19], v[44:45], v[22:23]
	v_pk_fma_f32 v[46:47], v[16:17], v[48:49], v[20:21]
	v_cvt_pk_bf16_f32 v40, v40, v41
	s_nop 0
	v_cvt_pk_bf16_f32 v41, v46, v47
	v_cvt_pk_bf16_f32 v43, v44, v45
	ds_write_b16 v188, v42
	ds_write_b16_d16_hi v188, v42 offset:272
	ds_write_b16 v188, v40 offset:544
	ds_write_b16_d16_hi v188, v40 offset:816
	ds_write_b16 v188, v41 offset:1088
	ds_write_b16_d16_hi v188, v41 offset:1360
	ds_write_b16 v188, v43 offset:1632
	ds_write_b16_d16_hi v188, v43 offset:1904
	s_cbranch_vccnz .LBB0_671
	ds_read_b64 v[40:41], v189
	v_lshlrev_b32_e32 v44, 16, v0
	v_and_b32_e32 v45, 0xffff0000, v0
	v_lshlrev_b32_e32 v42, 16, v1
	v_and_b32_e32 v43, 0xffff0000, v1
	v_lshlrev_b32_e32 v48, 16, v2
	v_and_b32_e32 v49, 0xffff0000, v2
	v_lshlrev_b32_e32 v46, 16, v3
	v_and_b32_e32 v47, 0xffff0000, v3
	s_waitcnt lgkmcnt(0)
	v_sub_f32_e32 v45, v45, v40
	v_sub_f32_e32 v44, v44, v40
	v_sub_f32_e32 v43, v43, v40
	v_sub_f32_e32 v42, v42, v40
	v_pk_mul_f32 v[44:45], v[40:41], v[44:45] op_sel:[1,0]
	v_sub_f32_e32 v47, v47, v40
	v_sub_f32_e32 v46, v46, v40
	v_sub_f32_e32 v49, v49, v40
	v_sub_f32_e32 v48, v48, v40
	v_pk_mul_f32 v[42:43], v[40:41], v[42:43] op_sel:[1,0]
	v_pk_fma_f32 v[44:45], v[24:25], v[44:45], v[28:29]
	v_pk_mul_f32 v[48:49], v[40:41], v[48:49] op_sel:[1,0]
	v_pk_mul_f32 v[40:41], v[40:41], v[46:47] op_sel:[1,0]
	v_pk_fma_f32 v[42:43], v[26:27], v[42:43], v[30:31]
	v_pk_fma_f32 v[40:41], v[18:19], v[40:41], v[22:23]
	v_cvt_pk_bf16_f32 v44, v44, v45
	v_pk_fma_f32 v[46:47], v[16:17], v[48:49], v[20:21]
	v_cvt_pk_bf16_f32 v42, v42, v43
	v_and_b32_e32 v45, 0xffff0000, v4
	v_cvt_pk_bf16_f32 v43, v46, v47
	v_cvt_pk_bf16_f32 v40, v40, v41
	ds_write_b16 v190, v44
	ds_write_b16_d16_hi v190, v44 offset:272
	ds_write_b16 v190, v42 offset:544
	ds_write_b16_d16_hi v190, v42 offset:816
	ds_write_b16 v190, v43 offset:1088
	ds_write_b16_d16_hi v190, v43 offset:1360
	ds_write_b16 v190, v40 offset:1632
	ds_write_b16_d16_hi v190, v40 offset:1904
	ds_read_b64 v[40:41], v191
	v_lshlrev_b32_e32 v42, 16, v5
	v_and_b32_e32 v43, 0xffff0000, v5
	v_lshlrev_b32_e32 v44, 16, v4
	v_lshlrev_b32_e32 v46, 16, v6
	s_waitcnt lgkmcnt(0)
	v_sub_f32_e32 v43, v43, v40
	v_sub_f32_e32 v42, v42, v40
	v_and_b32_e32 v47, 0xffff0000, v6
	v_sub_f32_e32 v45, v45, v40
	v_sub_f32_e32 v44, v44, v40
	v_pk_mul_f32 v[42:43], v[40:41], v[42:43] op_sel:[1,0]
	v_lshlrev_b32_e32 v48, 16, v7
	v_and_b32_e32 v49, 0xffff0000, v7
	v_pk_mul_f32 v[44:45], v[40:41], v[44:45] op_sel:[1,0]
	v_pk_fma_f32 v[26:27], v[26:27], v[42:43], v[30:31]
	v_sub_f32_e32 v31, v47, v40
	v_sub_f32_e32 v30, v46, v40
	v_pk_fma_f32 v[24:25], v[24:25], v[44:45], v[28:29]
	v_sub_f32_e32 v29, v49, v40
	v_sub_f32_e32 v28, v48, v40
	v_pk_mul_f32 v[30:31], v[40:41], v[30:31] op_sel:[1,0]
	v_pk_mul_f32 v[28:29], v[40:41], v[28:29] op_sel:[1,0]
	v_pk_fma_f32 v[16:17], v[16:17], v[30:31], v[20:21]
	v_cvt_pk_bf16_f32 v20, v24, v25
	v_pk_fma_f32 v[18:19], v[18:19], v[28:29], v[22:23]
	v_cvt_pk_bf16_f32 v21, v26, v27
	v_cvt_pk_bf16_f32 v16, v16, v17
	s_nop 0
	v_cvt_pk_bf16_f32 v17, v18, v19
	ds_write_b16 v192, v20
	ds_write_b16_d16_hi v192, v20 offset:272
	ds_write_b16 v192, v21 offset:544
	ds_write_b16_d16_hi v192, v21 offset:816
	ds_write_b16 v192, v16 offset:1088
	ds_write_b16_d16_hi v192, v16 offset:1360
	ds_write_b16 v192, v17 offset:1632
	ds_write_b16_d16_hi v192, v17 offset:1904
.LBB0_671:
	v_lshl_add_u64 v[114:115], v[112:113], 0, s[24:25]
	s_waitcnt lgkmcnt(0)
	s_barrier
	global_load_dwordx4 v[40:43], v[124:125], off offset:528
	global_load_dwordx4 v[48:51], v[124:125], off offset:512
	global_load_dwordx4 v[44:47], v[126:127], off offset:528
	global_load_dwordx4 v[52:55], v[126:127], off offset:512
	v_add_co_u32_e32 v16, vcc, 0x8000, v148
	s_waitcnt vmcnt(9)
	v_mov_b64_e32 v[28:29], v[36:37]
	v_addc_co_u32_e32 v17, vcc, 0, v149, vcc
	global_load_dwordx4 v[20:23], v[16:17], off
	s_nop 0
	global_load_dwordx4 v[16:19], v[16:17], off offset:64
	s_and_b64 vcc, exec, s[4:5]
	v_mov_b64_e32 v[30:31], v[38:39]
	s_cbranch_vccnz .LBB0_677
	v_add_co_u32_e32 v24, vcc, 0x8000, v148
	s_nop 1
	v_addc_co_u32_e32 v25, vcc, 0, v149, vcc
	global_load_dwordx4 v[28:31], v[24:25], off offset:128

; #define LAS __attribute__((address_space(3)))
; __global__ void __launch_bounds__(NTHR, 2) fwd_megakernel(Args args) {
;     ...
;                 if (h + 1 < 8) SGU_PREFETCH(h + 1);
;                 f32x4 a0 = (f32x4){0.f, 0.f, 0.f, 0.f}, a1 = a0;
; #pragma unroll
;                 for (int ks = 0; ks < 4; ++ks) if (ks < nk) {
;                     const int r0 = 16 * (2 * nq) + fr, r1 = r0 + 16, q = ks * 4 + fq;
;                     const bf16x8 x0 = *(const LAS bf16x8*)(Bc + r0 * LDB + ((q ^ ((r0 >> 3) & 15)) * 8)), x1 = *(const LAS bf16x8*)(Bc + r1 * LDB + ((q ^ ((r1 >> 3) & 15)) * 8));
;                     a0 = __builtin_amdgcn_mfma_f32_16x16x32_bf16(x0, cw[ks], a0, 0, 0, 0); a1 = __builtin_amdgcn_mfma_f32_16x16x32_bf16(x1, cw[ks], a1, 0, 0, 0);
;                 }
.LBB0_679:
	v_lshl_add_u64 v[160:161], s[20:21], 0, v[120:121]
	ds_read_b128 v[64:67], v193
	ds_read_b128 v[68:71], v194
	ds_read_b128 v[72:75], v195
	ds_read_b128 v[76:79], v196
	global_load_dword v120, v[160:161], off offset:512
	global_load_dwordx2 v[144:145], v[150:151], off offset:256
	global_load_dwordx2 v[142:143], v[150:151], off offset:288
	s_mov_b64 s[100:101], vcc
	v_lshl_add_u64 v[242:243], v[112:113], 0, s[24:25]
	global_load_dwordx4 v[238:241], v[112:113], off offset:512
	global_load_dwordx4 v[242:245], v[242:243], off offset:512
	s_mov_b64 vcc, s[4:5]
	s_cbranch_vccnz .Lgpv_g2
	v_lshlrev_b64 v[246:247], 11, v[152:153]
	v_lshl_add_u64 v[246:247], v[122:123], 0, v[246:247]
	v_lshl_add_u64 v[250:251], v[246:247], 0, s[24:25]
	global_load_dwordx4 v[246:249], v[246:247], off offset:512
	global_load_dwordx4 v[250:253], v[250:251], off offset:512
.Lgpv_g2:
	s_mov_b64 vcc, s[100:101]
	s_waitcnt lgkmcnt(3)
	v_mfma_f32_16x16x32_bf16 v[64:67], v[64:67], v[12:15], 0
	s_and_b64 vcc, exec, s[4:5]
	s_waitcnt lgkmcnt(2)
	v_mfma_f32_16x16x32_bf16 v[68:71], v[68:71], v[12:15], 0
	s_waitcnt lgkmcnt(1)
	v_mfma_f32_16x16x32_bf16 v[12:15], v[72:75], v[8:11], v[64:67]
	s_waitcnt lgkmcnt(0)
	v_mfma_f32_16x16x32_bf16 v[8:11], v[76:79], v[8:11], v[68:71]
	s_cbranch_vccnz .LBB0_681
	ds_read_b128 v[64:67], v197
	s_nop 1
	ds_read_b128 v[68:71], v198
	s_waitcnt lgkmcnt(1)
	v_mfma_f32_16x16x32_bf16 v[12:15], v[64:67], v[36:39], v[12:15]
	s_waitcnt lgkmcnt(0)
	v_mfma_f32_16x16x32_bf16 v[8:11], v[68:71], v[36:39], v[8:11]

; #define LAS __attribute__((address_space(3)))
; __device__ __forceinline__ unsigned cvt_pk_bf16(float lo, float hi) { unsigned r; asm volatile("v_cvt_pk_bf16_f32 %0, %1, %2" : "=v"(r) : "v"(lo), "v"(hi)); return r; }
; __device__ __forceinline__ float bf_lo(unsigned u) { return __uint_as_float(u << 16); }
; __device__ __forceinline__ float bf_hi(unsigned u) { return __uint_as_float(u & 0xffff0000u); }
; __global__ void __launch_bounds__(NTHR, 2) fwd_megakernel(Args args) {
;     ...
;                 for (int k = 0; k < 4; ++k) if (k < nk) { const int j = jb + 32 * k; const u32x4 v = pv[k]; const f32x2 ms = st[j];
;                     const f32x4 x0 = (f32x4){bf_lo(v.x), bf_hi(v.x), bf_lo(v.y), bf_hi(v.y)}, x1 = (f32x4){bf_lo(v.z), bf_hi(v.z), bf_lo(v.w), bf_hi(v.w)};
;                     const f32x4 y0 = (x0 - ms.x) * ms.y * pg0 + pb0, y1 = (x1 - ms.x) * ms.y * pg1 + pb1;
;                     LAS bf16_t* d = Bc + (c8 * 8) * LDB + (j ^ (8 * c8));
;                     const unsigned p0 = cvt_pk_bf16(y0[0], y0[1]), p1 = cvt_pk_bf16(y0[2], y0[3]), p2 = cvt_pk_bf16(y1[0], y1[1]), p3 = cvt_pk_bf16(y1[2], y1[3]);
;                     d[0 * LDB] = (bf16_t)(p0 & 0xffffu); d[1 * LDB] = (bf16_t)(p0 >> 16); d[2 * LDB] = (bf16_t)(p1 & 0xffffu); d[3 * LDB] = (bf16_t)(p1 >> 16);
;                     d[4 * LDB] = (bf16_t)(p2 & 0xffffu); d[5 * LDB] = (bf16_t)(p2 >> 16); d[6 * LDB] = (bf16_t)(p3 & 0xffffu); d[7 * LDB] = (bf16_t)(p3 >> 16); }
;                 bf16x8 cw[4];
; #pragma unroll
;                 for (int ks = 0; ks < 4; ++ks) cw[ks] = pw[ks];
;                 const u32x2 u0 = pu0, u1 = pu1; const float bs = pbs;
;                 __syncthreads();
;                 if (h + 1 < 8) SGU_PREFETCH(h + 1);
.LBB0_683:
	ds_read_b64 v[32:33], v181
	s_waitcnt vmcnt(12)
	v_lshlrev_b32_e32 v36, 16, v222
	v_and_b32_e32 v37, 0xffff0000, v222
	v_lshlrev_b32_e32 v34, 16, v223
	v_and_b32_e32 v35, 0xffff0000, v223
	v_lshlrev_b32_e32 v222, 16, v224
	v_and_b32_e32 v223, 0xffff0000, v224
	v_lshlrev_b32_e32 v38, 16, v225
	v_and_b32_e32 v39, 0xffff0000, v225
	s_waitcnt lgkmcnt(0)
	v_sub_f32_e32 v37, v37, v32
	v_sub_f32_e32 v36, v36, v32
	v_sub_f32_e32 v35, v35, v32
	v_sub_f32_e32 v34, v34, v32
	v_pk_mul_f32 v[36:37], v[32:33], v[36:37] op_sel:[1,0]
	v_sub_f32_e32 v39, v39, v32
	v_sub_f32_e32 v38, v38, v32
	v_sub_f32_e32 v223, v223, v32
	v_sub_f32_e32 v222, v222, v32
	v_pk_mul_f32 v[34:35], v[32:33], v[34:35] op_sel:[1,0]
	s_waitcnt vmcnt(7)
	v_pk_fma_f32 v[36:37], v[48:49], v[36:37], v[52:53]
	v_pk_mul_f32 v[222:223], v[32:33], v[222:223] op_sel:[1,0]
	v_pk_mul_f32 v[32:33], v[32:33], v[38:39] op_sel:[1,0]
	v_pk_fma_f32 v[34:35], v[50:51], v[34:35], v[54:55]
	v_pk_fma_f32 v[32:33], v[42:43], v[32:33], v[46:47]
	v_cvt_pk_bf16_f32 v36, v36, v37
	v_pk_fma_f32 v[38:39], v[40:41], v[222:223], v[44:45]
	v_cvt_pk_bf16_f32 v34, v34, v35
	v_and_b32_e32 v37, 0xffff0000, v226
	v_cvt_pk_bf16_f32 v35, v38, v39
	v_cvt_pk_bf16_f32 v32, v32, v33
	ds_write_b16 v186, v36 offset:34816
	ds_write_b16_d16_hi v186, v36 offset:35088
	ds_write_b16 v186, v34 offset:35360
	ds_write_b16_d16_hi v186, v34 offset:35632
	ds_write_b16 v186, v35 offset:35904
	ds_write_b16_d16_hi v186, v35 offset:36176
	ds_write_b16 v186, v32 offset:36448
	ds_write_b16_d16_hi v186, v32 offset:36720
	ds_read_b64 v[32:33], v187
	v_lshlrev_b32_e32 v36, 16, v226
	v_lshlrev_b32_e32 v34, 16, v227
	v_and_b32_e32 v35, 0xffff0000, v227
	v_lshlrev_b32_e32 v226, 16, v228
	v_and_b32_e32 v227, 0xffff0000, v228
	v_lshlrev_b32_e32 v38, 16, v229
	v_and_b32_e32 v39, 0xffff0000, v229
	s_waitcnt lgkmcnt(0)
	v_sub_f32_e32 v37, v37, v32
	v_sub_f32_e32 v36, v36, v32
	v_sub_f32_e32 v35, v35, v32
	v_sub_f32_e32 v34, v34, v32
	v_pk_mul_f32 v[36:37], v[32:33], v[36:37] op_sel:[1,0]
	v_sub_f32_e32 v39, v39, v32
	v_sub_f32_e32 v38, v38, v32
	v_sub_f32_e32 v227, v227, v32
	v_sub_f32_e32 v226, v226, v32
	v_pk_mul_f32 v[34:35], v[32:33], v[34:35] op_sel:[1,0]
	v_pk_fma_f32 v[36:37], v[48:49], v[36:37], v[52:53]
	v_pk_mul_f32 v[226:227], v[32:33], v[226:227] op_sel:[1,0]
	v_pk_mul_f32 v[32:33], v[32:33], v[38:39] op_sel:[1,0]
	v_pk_fma_f32 v[34:35], v[50:51], v[34:35], v[54:55]
	v_pk_fma_f32 v[32:33], v[42:43], v[32:33], v[46:47]
	v_cvt_pk_bf16_f32 v36, v36, v37
	s_and_b64 vcc, exec, s[4:5]
	v_pk_fma_f32 v[38:39], v[40:41], v[226:227], v[44:45]
	v_cvt_pk_bf16_f32 v34, v34, v35
	s_nop 0
	v_cvt_pk_bf16_f32 v35, v38, v39
	v_cvt_pk_bf16_f32 v32, v32, v33
	ds_write_b16 v188, v36 offset:34816
	ds_write_b16_d16_hi v188, v36 offset:35088
	ds_write_b16 v188, v34 offset:35360
	ds_write_b16_d16_hi v188, v34 offset:35632
	ds_write_b16 v188, v35 offset:35904
	ds_write_b16_d16_hi v188, v35 offset:36176
	ds_write_b16 v188, v32 offset:36448
	ds_write_b16_d16_hi v188, v32 offset:36720
	s_cbranch_vccnz .LBB0_685
	ds_read_b64 v[32:33], v189
	v_lshlrev_b32_e32 v36, 16, v230
	v_and_b32_e32 v37, 0xffff0000, v230
	v_lshlrev_b32_e32 v34, 16, v231
	v_and_b32_e32 v35, 0xffff0000, v231
	v_lshlrev_b32_e32 v226, 16, v232
	v_and_b32_e32 v227, 0xffff0000, v232
	v_lshlrev_b32_e32 v38, 16, v233
	v_and_b32_e32 v39, 0xffff0000, v233
	s_waitcnt lgkmcnt(0)
	v_sub_f32_e32 v37, v37, v32
	v_sub_f32_e32 v36, v36, v32
	v_sub_f32_e32 v35, v35, v32
	v_sub_f32_e32 v34, v34, v32
	v_pk_mul_f32 v[36:37], v[32:33], v[36:37] op_sel:[1,0]
	v_sub_f32_e32 v39, v39, v32
	v_sub_f32_e32 v38, v38, v32
	v_sub_f32_e32 v227, v227, v32
	v_sub_f32_e32 v226, v226, v32
	v_pk_mul_f32 v[34:35], v[32:33], v[34:35] op_sel:[1,0]
	v_pk_fma_f32 v[36:37], v[48:49], v[36:37], v[52:53]
	v_pk_mul_f32 v[226:227], v[32:33], v[226:227] op_sel:[1,0]
	v_pk_mul_f32 v[32:33], v[32:33], v[38:39] op_sel:[1,0]
	v_pk_fma_f32 v[34:35], v[50:51], v[34:35], v[54:55]
	v_pk_fma_f32 v[32:33], v[42:43], v[32:33], v[46:47]
	v_cvt_pk_bf16_f32 v36, v36, v37
	v_pk_fma_f32 v[38:39], v[40:41], v[226:227], v[44:45]
	v_cvt_pk_bf16_f32 v34, v34, v35
	v_and_b32_e32 v37, 0xffff0000, v234
	v_cvt_pk_bf16_f32 v35, v38, v39
	v_cvt_pk_bf16_f32 v32, v32, v33
	ds_write_b16 v190, v36 offset:34816
	ds_write_b16_d16_hi v190, v36 offset:35088
	ds_write_b16 v190, v34 offset:35360
	ds_write_b16_d16_hi v190, v34 offset:35632
	ds_write_b16 v190, v35 offset:35904
	ds_write_b16_d16_hi v190, v35 offset:36176
	ds_write_b16 v190, v32 offset:36448
	ds_write_b16_d16_hi v190, v32 offset:36720
	ds_read_b64 v[32:33], v191
	v_lshlrev_b32_e32 v36, 16, v234
	v_lshlrev_b32_e32 v34, 16, v235
	v_and_b32_e32 v35, 0xffff0000, v235
	v_lshlrev_b32_e32 v226, 16, v236
	s_waitcnt lgkmcnt(0)
	v_sub_f32_e32 v37, v37, v32
	v_sub_f32_e32 v36, v36, v32
	v_and_b32_e32 v227, 0xffff0000, v236
	v_lshlrev_b32_e32 v38, 16, v237
	v_and_b32_e32 v39, 0xffff0000, v237
	v_pk_mul_f32 v[36:37], v[32:33], v[36:37] op_sel:[1,0]
	v_sub_f32_e32 v35, v35, v32
	v_sub_f32_e32 v34, v34, v32
	v_pk_fma_f32 v[36:37], v[48:49], v[36:37], v[52:53]
	v_sub_f32_e32 v39, v39, v32
	v_sub_f32_e32 v38, v38, v32
	v_sub_f32_e32 v49, v227, v32
	v_sub_f32_e32 v48, v226, v32
	v_pk_mul_f32 v[34:35], v[32:33], v[34:35] op_sel:[1,0]
	v_pk_mul_f32 v[48:49], v[32:33], v[48:49] op_sel:[1,0]
	v_pk_mul_f32 v[32:33], v[32:33], v[38:39] op_sel:[1,0]
	v_pk_fma_f32 v[34:35], v[50:51], v[34:35], v[54:55]
	v_pk_fma_f32 v[32:33], v[42:43], v[32:33], v[46:47]
	v_cvt_pk_bf16_f32 v36, v36, v37
	v_pk_fma_f32 v[38:39], v[40:41], v[48:49], v[44:45]
	v_cvt_pk_bf16_f32 v34, v34, v35
	s_nop 0
	v_cvt_pk_bf16_f32 v35, v38, v39
	v_cvt_pk_bf16_f32 v32, v32, v33
	ds_write_b16 v192, v36 offset:34816
	ds_write_b16_d16_hi v192, v36 offset:35088
	ds_write_b16 v192, v34 offset:35360
	ds_write_b16_d16_hi v192, v34 offset:35632
	ds_write_b16 v192, v35 offset:35904
	ds_write_b16_d16_hi v192, v35 offset:36176
	ds_write_b16 v192, v32 offset:36448
	ds_write_b16_d16_hi v192, v32 offset:36720
.LBB0_685:
	s_waitcnt lgkmcnt(0)
	s_barrier
	global_load_dwordx4 v[36:39], v[124:125], off offset:1040
	global_load_dwordx4 v[52:55], v[124:125], off offset:1024
	global_load_dwordx4 v[48:51], v[126:127], off offset:1040
	global_load_dwordx4 v[60:63], v[126:127], off offset:1024
	v_add_co_u32_e32 v32, vcc, 0x10000, v148
	s_waitcnt vmcnt(9)
	v_mov_b64_e32 v[46:47], v[30:31]
	v_addc_co_u32_e32 v33, vcc, 0, v149, vcc
	global_load_dwordx4 v[56:59], v[32:33], off
	global_load_dwordx4 v[40:43], v[32:33], off offset:64
	s_and_b64 vcc, exec, s[4:5]
	v_mov_b64_e32 v[44:45], v[28:29]
	s_cbranch_vccnz .LBB0_691
	v_add_co_u32_e32 v32, vcc, 0x10000, v148
	s_nop 1
	v_addc_co_u32_e32 v33, vcc, 0, v149, vcc
	global_load_dwordx4 v[44:47], v[32:33], off offset:128

; #define LAS __attribute__((address_space(3)))
; __global__ void __launch_bounds__(NTHR, 2) fwd_megakernel(Args args) {
;     ...
;                 f32x4 a0 = (f32x4){0.f, 0.f, 0.f, 0.f}, a1 = a0;
; #pragma unroll
;                 for (int ks = 0; ks < 4; ++ks) if (ks < nk) {
;                     const int r0 = 16 * (2 * nq) + fr, r1 = r0 + 16, q = ks * 4 + fq;
;                     const bf16x8 x0 = *(const LAS bf16x8*)(Bc + r0 * LDB + ((q ^ ((r0 >> 3) & 15)) * 8)), x1 = *(const LAS bf16x8*)(Bc + r1 * LDB + ((q ^ ((r1 >> 3) & 15)) * 8));
;                     a0 = __builtin_amdgcn_mfma_f32_16x16x32_bf16(x0, cw[ks], a0, 0, 0, 0); a1 = __builtin_amdgcn_mfma_f32_16x16x32_bf16(x1, cw[ks], a1, 0, 0, 0);
;                 }
.LBB0_693:
	ds_read_b128 v[72:75], v193 offset:34816
	ds_read_b128 v[76:79], v194 offset:34816
	global_load_dword v154, v[160:161], off offset:1024
	s_and_b64 vcc, exec, s[4:5]
	s_waitcnt lgkmcnt(1)
	v_mfma_f32_16x16x32_bf16 v[72:75], v[72:75], v[20:23], 0
	ds_read_b128 v[80:83], v196 offset:34816
	s_waitcnt lgkmcnt(1)
	v_mfma_f32_16x16x32_bf16 v[76:79], v[76:79], v[20:23], 0
	ds_read_b128 v[20:23], v195 offset:34816
	global_load_dwordx2 v[158:159], v[150:151], off offset:512
	global_load_dwordx2 v[156:157], v[150:151], off offset:544
	s_mov_b64 s[100:101], vcc
	v_lshl_add_u64 v[226:227], v[112:113], 0, s[24:25]
	global_load_dwordx4 v[222:225], v[112:113], off offset:768
	global_load_dwordx4 v[226:229], v[226:227], off offset:768
	s_mov_b64 vcc, s[4:5]
	s_cbranch_vccnz .Lgpv_g3
	v_lshlrev_b64 v[230:231], 11, v[152:153]
	v_lshl_add_u64 v[230:231], v[122:123], 0, v[230:231]
	v_lshl_add_u64 v[234:235], v[230:231], 0, s[24:25]
	global_load_dwordx4 v[230:233], v[230:231], off offset:768
	global_load_dwordx4 v[234:237], v[234:235], off offset:768
.Lgpv_g3:
	s_mov_b64 vcc, s[100:101]
	s_waitcnt lgkmcnt(0)
	v_mfma_f32_16x16x32_bf16 v[20:23], v[20:23], v[16:19], v[72:75]
	v_mfma_f32_16x16x32_bf16 v[16:19], v[80:83], v[16:19], v[76:79]
	s_cbranch_vccnz .LBB0_695
	s_nop 0
	ds_read_b128 v[72:75], v197 offset:34816
	ds_read_b128 v[76:79], v198 offset:34816
	s_waitcnt lgkmcnt(1)
	v_mfma_f32_16x16x32_bf16 v[20:23], v[72:75], v[28:31], v[20:23]
	s_waitcnt lgkmcnt(0)
	v_mfma_f32_16x16x32_bf16 v[16:19], v[76:79], v[28:31], v[16:19]

; #define LAS __attribute__((address_space(3)))
; __device__ __forceinline__ unsigned cvt_pk_bf16(float lo, float hi) { unsigned r; asm volatile("v_cvt_pk_bf16_f32 %0, %1, %2" : "=v"(r) : "v"(lo), "v"(hi)); return r; }
; __device__ __forceinline__ float bf_lo(unsigned u) { return __uint_as_float(u << 16); }
; __device__ __forceinline__ float bf_hi(unsigned u) { return __uint_as_float(u & 0xffff0000u); }
; __global__ void __launch_bounds__(NTHR, 2) fwd_megakernel(Args args) {
;     ...
;                 for (int k = 0; k < 4; ++k) if (k < nk) { const int j = jb + 32 * k; const u32x4 v = pv[k]; const f32x2 ms = st[j];
;                     const f32x4 x0 = (f32x4){bf_lo(v.x), bf_hi(v.x), bf_lo(v.y), bf_hi(v.y)}, x1 = (f32x4){bf_lo(v.z), bf_hi(v.z), bf_lo(v.w), bf_hi(v.w)};
;                     const f32x4 y0 = (x0 - ms.x) * ms.y * pg0 + pb0, y1 = (x1 - ms.x) * ms.y * pg1 + pb1;
;                     LAS bf16_t* d = Bc + (c8 * 8) * LDB + (j ^ (8 * c8));
;                     const unsigned p0 = cvt_pk_bf16(y0[0], y0[1]), p1 = cvt_pk_bf16(y0[2], y0[3]), p2 = cvt_pk_bf16(y1[0], y1[1]), p3 = cvt_pk_bf16(y1[2], y1[3]);
;                     d[0 * LDB] = (bf16_t)(p0 & 0xffffu); d[1 * LDB] = (bf16_t)(p0 >> 16); d[2 * LDB] = (bf16_t)(p1 & 0xffffu); d[3 * LDB] = (bf16_t)(p1 >> 16);
;                     d[4 * LDB] = (bf16_t)(p2 & 0xffffu); d[5 * LDB] = (bf16_t)(p2 >> 16); d[6 * LDB] = (bf16_t)(p3 & 0xffffu); d[7 * LDB] = (bf16_t)(p3 >> 16); }
;                 bf16x8 cw[4];
; #pragma unroll
;                 for (int ks = 0; ks < 4; ++ks) cw[ks] = pw[ks];
;                 const u32x2 u0 = pu0, u1 = pu1; const float bs = pbs;
;                 __syncthreads();
;                 if (h + 1 < 8) SGU_PREFETCH(h + 1);
.LBB0_697:
	ds_read_b64 v[24:25], v181
	s_waitcnt vmcnt(12)
	v_lshlrev_b32_e32 v28, 16, v238
	v_and_b32_e32 v29, 0xffff0000, v238
	v_lshlrev_b32_e32 v26, 16, v239
	v_and_b32_e32 v27, 0xffff0000, v239
	v_lshlrev_b32_e32 v238, 16, v240
	v_and_b32_e32 v239, 0xffff0000, v240
	v_lshlrev_b32_e32 v30, 16, v241
	v_and_b32_e32 v31, 0xffff0000, v241
	s_waitcnt lgkmcnt(0)
	v_sub_f32_e32 v29, v29, v24
	v_sub_f32_e32 v28, v28, v24
	v_sub_f32_e32 v27, v27, v24
	v_sub_f32_e32 v26, v26, v24
	v_pk_mul_f32 v[28:29], v[24:25], v[28:29] op_sel:[1,0]
	v_sub_f32_e32 v31, v31, v24
	v_sub_f32_e32 v30, v30, v24
	v_sub_f32_e32 v239, v239, v24
	v_sub_f32_e32 v238, v238, v24
	v_pk_mul_f32 v[26:27], v[24:25], v[26:27] op_sel:[1,0]
	s_waitcnt vmcnt(7)
	v_pk_fma_f32 v[28:29], v[52:53], v[28:29], v[60:61]
	v_pk_mul_f32 v[238:239], v[24:25], v[238:239] op_sel:[1,0]
	v_pk_mul_f32 v[24:25], v[24:25], v[30:31] op_sel:[1,0]
	v_pk_fma_f32 v[26:27], v[54:55], v[26:27], v[62:63]
	v_pk_fma_f32 v[24:25], v[38:39], v[24:25], v[50:51]
	v_cvt_pk_bf16_f32 v28, v28, v29
	v_pk_fma_f32 v[30:31], v[36:37], v[238:239], v[48:49]
	v_cvt_pk_bf16_f32 v26, v26, v27
	v_and_b32_e32 v29, 0xffff0000, v242
	v_cvt_pk_bf16_f32 v27, v30, v31
	v_cvt_pk_bf16_f32 v24, v24, v25
	ds_write_b16 v186, v28
	ds_write_b16_d16_hi v186, v28 offset:272
	ds_write_b16 v186, v26 offset:544
	ds_write_b16_d16_hi v186, v26 offset:816
	ds_write_b16 v186, v27 offset:1088
	ds_write_b16_d16_hi v186, v27 offset:1360
	ds_write_b16 v186, v24 offset:1632
	ds_write_b16_d16_hi v186, v24 offset:1904
	ds_read_b64 v[24:25], v187
	v_lshlrev_b32_e32 v28, 16, v242
	v_lshlrev_b32_e32 v26, 16, v243
	v_and_b32_e32 v27, 0xffff0000, v243
	v_lshlrev_b32_e32 v242, 16, v244
	v_and_b32_e32 v243, 0xffff0000, v244
	v_lshlrev_b32_e32 v30, 16, v245
	v_and_b32_e32 v31, 0xffff0000, v245
	s_waitcnt lgkmcnt(0)
	v_sub_f32_e32 v29, v29, v24
	v_sub_f32_e32 v28, v28, v24
	v_sub_f32_e32 v27, v27, v24
	v_sub_f32_e32 v26, v26, v24
	v_pk_mul_f32 v[28:29], v[24:25], v[28:29] op_sel:[1,0]
	v_sub_f32_e32 v31, v31, v24
	v_sub_f32_e32 v30, v30, v24
	v_sub_f32_e32 v243, v243, v24
	v_sub_f32_e32 v242, v242, v24
	v_pk_mul_f32 v[26:27], v[24:25], v[26:27] op_sel:[1,0]
	v_pk_fma_f32 v[28:29], v[52:53], v[28:29], v[60:61]
	v_pk_mul_f32 v[242:243], v[24:25], v[242:243] op_sel:[1,0]
	v_pk_mul_f32 v[24:25], v[24:25], v[30:31] op_sel:[1,0]
	v_pk_fma_f32 v[26:27], v[54:55], v[26:27], v[62:63]
	v_pk_fma_f32 v[24:25], v[38:39], v[24:25], v[50:51]
	v_cvt_pk_bf16_f32 v28, v28, v29
	s_and_b64 vcc, exec, s[4:5]
	v_pk_fma_f32 v[30:31], v[36:37], v[242:243], v[48:49]
	v_cvt_pk_bf16_f32 v26, v26, v27
	s_nop 0
	v_cvt_pk_bf16_f32 v27, v30, v31
	v_cvt_pk_bf16_f32 v24, v24, v25
	ds_write_b16 v188, v28
	ds_write_b16_d16_hi v188, v28 offset:272
	ds_write_b16 v188, v26 offset:544
	ds_write_b16_d16_hi v188, v26 offset:816
	ds_write_b16 v188, v27 offset:1088
	ds_write_b16_d16_hi v188, v27 offset:1360
	ds_write_b16 v188, v24 offset:1632
	ds_write_b16_d16_hi v188, v24 offset:1904
	s_cbranch_vccnz .LBB0_699
	ds_read_b64 v[24:25], v189
	v_lshlrev_b32_e32 v28, 16, v246
	v_and_b32_e32 v29, 0xffff0000, v246
	v_lshlrev_b32_e32 v26, 16, v247
	v_and_b32_e32 v27, 0xffff0000, v247
	v_lshlrev_b32_e32 v242, 16, v248
	v_and_b32_e32 v243, 0xffff0000, v248
	v_lshlrev_b32_e32 v30, 16, v249
	v_and_b32_e32 v31, 0xffff0000, v249
	s_waitcnt lgkmcnt(0)
	v_sub_f32_e32 v29, v29, v24
	v_sub_f32_e32 v28, v28, v24
	v_sub_f32_e32 v27, v27, v24
	v_sub_f32_e32 v26, v26, v24
	v_pk_mul_f32 v[28:29], v[24:25], v[28:29] op_sel:[1,0]
	v_sub_f32_e32 v31, v31, v24
	v_sub_f32_e32 v30, v30, v24
	v_sub_f32_e32 v243, v243, v24
	v_sub_f32_e32 v242, v242, v24
	v_pk_mul_f32 v[26:27], v[24:25], v[26:27] op_sel:[1,0]
	v_pk_fma_f32 v[28:29], v[52:53], v[28:29], v[60:61]
	v_pk_mul_f32 v[242:243], v[24:25], v[242:243] op_sel:[1,0]
	v_pk_mul_f32 v[24:25], v[24:25], v[30:31] op_sel:[1,0]
	v_pk_fma_f32 v[26:27], v[54:55], v[26:27], v[62:63]
	v_pk_fma_f32 v[24:25], v[38:39], v[24:25], v[50:51]
	v_cvt_pk_bf16_f32 v28, v28, v29
	v_pk_fma_f32 v[30:31], v[36:37], v[242:243], v[48:49]
	v_cvt_pk_bf16_f32 v26, v26, v27
	v_and_b32_e32 v29, 0xffff0000, v250
	v_cvt_pk_bf16_f32 v27, v30, v31
	v_cvt_pk_bf16_f32 v24, v24, v25
	ds_write_b16 v190, v28
	ds_write_b16_d16_hi v190, v28 offset:272
	ds_write_b16 v190, v26 offset:544
	ds_write_b16_d16_hi v190, v26 offset:816
	ds_write_b16 v190, v27 offset:1088
	ds_write_b16_d16_hi v190, v27 offset:1360
	ds_write_b16 v190, v24 offset:1632
	ds_write_b16_d16_hi v190, v24 offset:1904
	ds_read_b64 v[24:25], v191
	v_lshlrev_b32_e32 v28, 16, v250
	v_lshlrev_b32_e32 v26, 16, v251
	v_and_b32_e32 v27, 0xffff0000, v251
	v_lshlrev_b32_e32 v242, 16, v252
	s_waitcnt lgkmcnt(0)
	v_sub_f32_e32 v29, v29, v24
	v_sub_f32_e32 v28, v28, v24
	v_and_b32_e32 v243, 0xffff0000, v252
	v_lshlrev_b32_e32 v30, 16, v253
	v_and_b32_e32 v31, 0xffff0000, v253
	v_pk_mul_f32 v[28:29], v[24:25], v[28:29] op_sel:[1,0]
	v_sub_f32_e32 v27, v27, v24
	v_sub_f32_e32 v26, v26, v24
	v_pk_fma_f32 v[28:29], v[52:53], v[28:29], v[60:61]
	v_sub_f32_e32 v31, v31, v24
	v_sub_f32_e32 v30, v30, v24
	v_sub_f32_e32 v53, v243, v24
	v_sub_f32_e32 v52, v242, v24
	v_pk_mul_f32 v[26:27], v[24:25], v[26:27] op_sel:[1,0]
	v_pk_mul_f32 v[52:53], v[24:25], v[52:53] op_sel:[1,0]
	v_pk_mul_f32 v[24:25], v[24:25], v[30:31] op_sel:[1,0]
	v_pk_fma_f32 v[26:27], v[54:55], v[26:27], v[62:63]
	v_pk_fma_f32 v[24:25], v[38:39], v[24:25], v[50:51]
	v_cvt_pk_bf16_f32 v28, v28, v29
	v_pk_fma_f32 v[30:31], v[36:37], v[52:53], v[48:49]
	v_cvt_pk_bf16_f32 v26, v26, v27
	s_nop 0
	v_cvt_pk_bf16_f32 v27, v30, v31
	v_cvt_pk_bf16_f32 v24, v24, v25
	ds_write_b16 v192, v28
	ds_write_b16_d16_hi v192, v28 offset:272
	ds_write_b16 v192, v26 offset:544
	ds_write_b16_d16_hi v192, v26 offset:816
	ds_write_b16 v192, v27 offset:1088
	ds_write_b16_d16_hi v192, v27 offset:1360
	ds_write_b16 v192, v24 offset:1632
	ds_write_b16_d16_hi v192, v24 offset:1904
.LBB0_699:
	s_waitcnt lgkmcnt(0)
	s_barrier
	global_load_dwordx4 v[60:63], v[124:125], off offset:1552
	global_load_dwordx4 v[72:75], v[124:125], off offset:1536
	global_load_dwordx4 v[68:71], v[126:127], off offset:1552
	global_load_dwordx4 v[76:79], v[126:127], off offset:1536
	v_add_co_u32_e32 v24, vcc, 0x18000, v148
	s_waitcnt vmcnt(9)
	v_mov_b64_e32 v[54:55], v[46:47]
	v_addc_co_u32_e32 v25, vcc, 0, v149, vcc
	global_load_dwordx4 v[64:67], v[24:25], off
	global_load_dwordx4 v[48:51], v[24:25], off offset:64
	s_and_b64 vcc, exec, s[4:5]
	v_mov_b64_e32 v[52:53], v[44:45]
	s_cbranch_vccnz .LBB0_705
	v_add_co_u32_e32 v24, vcc, 0x18000, v148
	s_nop 1
	v_addc_co_u32_e32 v25, vcc, 0, v149, vcc
	global_load_dwordx4 v[52:55], v[24:25], off offset:128

; #define LAS __attribute__((address_space(3)))
; __global__ void __launch_bounds__(NTHR, 2) fwd_megakernel(Args args) {
;     ...
;                 f32x4 a0 = (f32x4){0.f, 0.f, 0.f, 0.f}, a1 = a0;
; #pragma unroll
;                 for (int ks = 0; ks < 4; ++ks) if (ks < nk) {
;                     const int r0 = 16 * (2 * nq) + fr, r1 = r0 + 16, q = ks * 4 + fq;
;                     const bf16x8 x0 = *(const LAS bf16x8*)(Bc + r0 * LDB + ((q ^ ((r0 >> 3) & 15)) * 8)), x1 = *(const LAS bf16x8*)(Bc + r1 * LDB + ((q ^ ((r1 >> 3) & 15)) * 8));
;                     a0 = __builtin_amdgcn_mfma_f32_16x16x32_bf16(x0, cw[ks], a0, 0, 0, 0); a1 = __builtin_amdgcn_mfma_f32_16x16x32_bf16(x1, cw[ks], a1, 0, 0, 0);
;                 }
.LBB0_707:
	ds_read_b128 v[24:27], v193
	ds_read_b128 v[28:31], v194
	global_load_dword v162, v[160:161], off offset:1536
	s_and_b64 vcc, exec, s[4:5]
	s_waitcnt lgkmcnt(1)
	v_mfma_f32_16x16x32_bf16 v[24:27], v[24:27], v[56:59], 0
	ds_read_b128 v[88:91], v196
	s_waitcnt lgkmcnt(1)
	v_mfma_f32_16x16x32_bf16 v[56:59], v[28:31], v[56:59], 0
	ds_read_b128 v[28:31], v195
	global_load_dwordx2 v[166:167], v[150:151], off offset:768
	global_load_dwordx2 v[164:165], v[150:151], off offset:800
	s_mov_b64 s[100:101], vcc
	v_lshl_add_u64 v[242:243], v[112:113], 0, s[24:25]
	global_load_dwordx4 v[238:241], v[112:113], off offset:1024
	global_load_dwordx4 v[242:245], v[242:243], off offset:1024
	s_mov_b64 vcc, s[4:5]
	s_cbranch_vccnz .Lgpv_g4
	v_lshlrev_b64 v[246:247], 11, v[152:153]
	v_lshl_add_u64 v[246:247], v[122:123], 0, v[246:247]
	v_lshl_add_u64 v[250:251], v[246:247], 0, s[24:25]
	global_load_dwordx4 v[246:249], v[246:247], off offset:1024
	global_load_dwordx4 v[250:253], v[250:251], off offset:1024
.Lgpv_g4:
	s_mov_b64 vcc, s[100:101]
	s_waitcnt lgkmcnt(0)
	v_mfma_f32_16x16x32_bf16 v[28:31], v[28:31], v[40:43], v[24:27]
	v_mfma_f32_16x16x32_bf16 v[24:27], v[88:91], v[40:43], v[56:59]
	s_cbranch_vccnz .LBB0_709
	ds_read_b128 v[40:43], v197
	s_nop 0
	ds_read_b128 v[56:59], v198
	s_waitcnt lgkmcnt(1)
	v_mfma_f32_16x16x32_bf16 v[28:31], v[40:43], v[44:47], v[28:31]
	s_waitcnt lgkmcnt(0)
	v_mfma_f32_16x16x32_bf16 v[24:27], v[56:59], v[44:47], v[24:27]

; #define LAS __attribute__((address_space(3)))
; __device__ __forceinline__ unsigned cvt_pk_bf16(float lo, float hi) { unsigned r; asm volatile("v_cvt_pk_bf16_f32 %0, %1, %2" : "=v"(r) : "v"(lo), "v"(hi)); return r; }
; __device__ __forceinline__ float bf_lo(unsigned u) { return __uint_as_float(u << 16); }
; __device__ __forceinline__ float bf_hi(unsigned u) { return __uint_as_float(u & 0xffff0000u); }
; __global__ void __launch_bounds__(NTHR, 2) fwd_megakernel(Args args) {
;     ...
;                 for (int k = 0; k < 4; ++k) if (k < nk) { const int j = jb + 32 * k; const u32x4 v = pv[k]; const f32x2 ms = st[j];
;                     const f32x4 x0 = (f32x4){bf_lo(v.x), bf_hi(v.x), bf_lo(v.y), bf_hi(v.y)}, x1 = (f32x4){bf_lo(v.z), bf_hi(v.z), bf_lo(v.w), bf_hi(v.w)};
;                     const f32x4 y0 = (x0 - ms.x) * ms.y * pg0 + pb0, y1 = (x1 - ms.x) * ms.y * pg1 + pb1;
;                     LAS bf16_t* d = Bc + (c8 * 8) * LDB + (j ^ (8 * c8));
;                     const unsigned p0 = cvt_pk_bf16(y0[0], y0[1]), p1 = cvt_pk_bf16(y0[2], y0[3]), p2 = cvt_pk_bf16(y1[0], y1[1]), p3 = cvt_pk_bf16(y1[2], y1[3]);
;                     d[0 * LDB] = (bf16_t)(p0 & 0xffffu); d[1 * LDB] = (bf16_t)(p0 >> 16); d[2 * LDB] = (bf16_t)(p1 & 0xffffu); d[3 * LDB] = (bf16_t)(p1 >> 16);
;                     d[4 * LDB] = (bf16_t)(p2 & 0xffffu); d[5 * LDB] = (bf16_t)(p2 >> 16); d[6 * LDB] = (bf16_t)(p3 & 0xffffu); d[7 * LDB] = (bf16_t)(p3 >> 16); }
;                 bf16x8 cw[4];
; #pragma unroll
;                 for (int ks = 0; ks < 4; ++ks) cw[ks] = pw[ks];
;                 const u32x2 u0 = pu0, u1 = pu1; const float bs = pbs;
;                 __syncthreads();
;                 if (h + 1 < 8) SGU_PREFETCH(h + 1);
.LBB0_711:
	ds_read_b64 v[32:33], v181
	s_waitcnt vmcnt(12)
	v_lshlrev_b32_e32 v40, 16, v222
	v_and_b32_e32 v41, 0xffff0000, v222
	v_lshlrev_b32_e32 v34, 16, v223
	v_and_b32_e32 v35, 0xffff0000, v223
	v_lshlrev_b32_e32 v44, 16, v224
	v_and_b32_e32 v45, 0xffff0000, v224
	v_lshlrev_b32_e32 v42, 16, v225
	v_and_b32_e32 v43, 0xffff0000, v225
	s_waitcnt lgkmcnt(0)
	v_sub_f32_e32 v41, v41, v32
	v_sub_f32_e32 v40, v40, v32
	v_sub_f32_e32 v35, v35, v32
	v_sub_f32_e32 v34, v34, v32
	v_pk_mul_f32 v[40:41], v[32:33], v[40:41] op_sel:[1,0]
	v_sub_f32_e32 v43, v43, v32
	v_sub_f32_e32 v42, v42, v32
	v_sub_f32_e32 v45, v45, v32
	v_sub_f32_e32 v44, v44, v32
	v_pk_mul_f32 v[34:35], v[32:33], v[34:35] op_sel:[1,0]
	s_waitcnt vmcnt(7)
	v_pk_fma_f32 v[40:41], v[72:73], v[40:41], v[76:77]
	v_pk_mul_f32 v[44:45], v[32:33], v[44:45] op_sel:[1,0]
	v_pk_mul_f32 v[32:33], v[32:33], v[42:43] op_sel:[1,0]
	v_pk_fma_f32 v[34:35], v[74:75], v[34:35], v[78:79]
	v_pk_fma_f32 v[32:33], v[62:63], v[32:33], v[70:71]
	v_cvt_pk_bf16_f32 v40, v40, v41
	v_pk_fma_f32 v[42:43], v[60:61], v[44:45], v[68:69]
	v_cvt_pk_bf16_f32 v34, v34, v35
	v_and_b32_e32 v41, 0xffff0000, v226
	v_cvt_pk_bf16_f32 v35, v42, v43
	v_cvt_pk_bf16_f32 v32, v32, v33
	ds_write_b16 v186, v40 offset:34816
	ds_write_b16_d16_hi v186, v40 offset:35088
	ds_write_b16 v186, v34 offset:35360
	ds_write_b16_d16_hi v186, v34 offset:35632
	ds_write_b16 v186, v35 offset:35904
	ds_write_b16_d16_hi v186, v35 offset:36176
	ds_write_b16 v186, v32 offset:36448
	ds_write_b16_d16_hi v186, v32 offset:36720
	ds_read_b64 v[32:33], v187
	v_lshlrev_b32_e32 v40, 16, v226
	v_lshlrev_b32_e32 v34, 16, v227
	v_and_b32_e32 v35, 0xffff0000, v227
	v_lshlrev_b32_e32 v44, 16, v228
	v_and_b32_e32 v45, 0xffff0000, v228
	v_lshlrev_b32_e32 v42, 16, v229
	v_and_b32_e32 v43, 0xffff0000, v229
	s_waitcnt lgkmcnt(0)
	v_sub_f32_e32 v41, v41, v32
	v_sub_f32_e32 v40, v40, v32
	v_sub_f32_e32 v35, v35, v32
	v_sub_f32_e32 v34, v34, v32
	v_pk_mul_f32 v[40:41], v[32:33], v[40:41] op_sel:[1,0]
	v_sub_f32_e32 v43, v43, v32
	v_sub_f32_e32 v42, v42, v32
	v_sub_f32_e32 v45, v45, v32
	v_sub_f32_e32 v44, v44, v32
	v_pk_mul_f32 v[34:35], v[32:33], v[34:35] op_sel:[1,0]
	v_pk_fma_f32 v[40:41], v[72:73], v[40:41], v[76:77]
	v_pk_mul_f32 v[44:45], v[32:33], v[44:45] op_sel:[1,0]
	v_pk_mul_f32 v[32:33], v[32:33], v[42:43] op_sel:[1,0]
	v_pk_fma_f32 v[34:35], v[74:75], v[34:35], v[78:79]
	v_pk_fma_f32 v[32:33], v[62:63], v[32:33], v[70:71]
	v_cvt_pk_bf16_f32 v40, v40, v41
	s_and_b64 vcc, exec, s[4:5]
	v_pk_fma_f32 v[42:43], v[60:61], v[44:45], v[68:69]
	v_cvt_pk_bf16_f32 v34, v34, v35
	s_nop 0
	v_cvt_pk_bf16_f32 v35, v42, v43
	v_cvt_pk_bf16_f32 v32, v32, v33
	ds_write_b16 v188, v40 offset:34816
	ds_write_b16_d16_hi v188, v40 offset:35088
	ds_write_b16 v188, v34 offset:35360
	ds_write_b16_d16_hi v188, v34 offset:35632
	ds_write_b16 v188, v35 offset:35904
	ds_write_b16_d16_hi v188, v35 offset:36176
	ds_write_b16 v188, v32 offset:36448
	ds_write_b16_d16_hi v188, v32 offset:36720
	s_cbranch_vccnz .LBB0_713
	ds_read_b64 v[32:33], v189
	v_lshlrev_b32_e32 v40, 16, v230
	v_and_b32_e32 v41, 0xffff0000, v230
	v_lshlrev_b32_e32 v34, 16, v231
	v_and_b32_e32 v35, 0xffff0000, v231
	v_lshlrev_b32_e32 v44, 16, v232
	v_and_b32_e32 v45, 0xffff0000, v232
	v_lshlrev_b32_e32 v42, 16, v233
	v_and_b32_e32 v43, 0xffff0000, v233
	s_waitcnt lgkmcnt(0)
	v_sub_f32_e32 v41, v41, v32
	v_sub_f32_e32 v40, v40, v32
	v_sub_f32_e32 v35, v35, v32
	v_sub_f32_e32 v34, v34, v32
	v_pk_mul_f32 v[40:41], v[32:33], v[40:41] op_sel:[1,0]
	v_sub_f32_e32 v43, v43, v32
	v_sub_f32_e32 v42, v42, v32
	v_sub_f32_e32 v45, v45, v32
	v_sub_f32_e32 v44, v44, v32
	v_pk_mul_f32 v[34:35], v[32:33], v[34:35] op_sel:[1,0]
	v_pk_fma_f32 v[40:41], v[72:73], v[40:41], v[76:77]
	v_pk_mul_f32 v[44:45], v[32:33], v[44:45] op_sel:[1,0]
	v_pk_mul_f32 v[32:33], v[32:33], v[42:43] op_sel:[1,0]
	v_pk_fma_f32 v[34:35], v[74:75], v[34:35], v[78:79]
	v_pk_fma_f32 v[32:33], v[62:63], v[32:33], v[70:71]
	v_cvt_pk_bf16_f32 v40, v40, v41
	v_pk_fma_f32 v[42:43], v[60:61], v[44:45], v[68:69]
	v_cvt_pk_bf16_f32 v34, v34, v35
	v_and_b32_e32 v41, 0xffff0000, v234
	v_cvt_pk_bf16_f32 v35, v42, v43
	v_cvt_pk_bf16_f32 v32, v32, v33
	ds_write_b16 v190, v40 offset:34816
	ds_write_b16_d16_hi v190, v40 offset:35088
	ds_write_b16 v190, v34 offset:35360
	ds_write_b16_d16_hi v190, v34 offset:35632
	ds_write_b16 v190, v35 offset:35904
	ds_write_b16_d16_hi v190, v35 offset:36176
	ds_write_b16 v190, v32 offset:36448
	ds_write_b16_d16_hi v190, v32 offset:36720
	ds_read_b64 v[32:33], v191
	v_lshlrev_b32_e32 v40, 16, v234
	v_lshlrev_b32_e32 v34, 16, v235
	v_and_b32_e32 v35, 0xffff0000, v235
	v_lshlrev_b32_e32 v44, 16, v236
	v_and_b32_e32 v45, 0xffff0000, v236
	v_lshlrev_b32_e32 v42, 16, v237
	v_and_b32_e32 v43, 0xffff0000, v237
	s_waitcnt lgkmcnt(0)
	v_sub_f32_e32 v41, v41, v32
	v_sub_f32_e32 v40, v40, v32
	v_sub_f32_e32 v35, v35, v32
	v_sub_f32_e32 v34, v34, v32
	v_pk_mul_f32 v[40:41], v[32:33], v[40:41] op_sel:[1,0]
	v_sub_f32_e32 v43, v43, v32
	v_sub_f32_e32 v42, v42, v32
	v_sub_f32_e32 v45, v45, v32
	v_sub_f32_e32 v44, v44, v32
	v_pk_mul_f32 v[34:35], v[32:33], v[34:35] op_sel:[1,0]
	v_pk_fma_f32 v[40:41], v[72:73], v[40:41], v[76:77]
	v_pk_mul_f32 v[44:45], v[32:33], v[44:45] op_sel:[1,0]
	v_pk_mul_f32 v[32:33], v[32:33], v[42:43] op_sel:[1,0]
	v_pk_fma_f32 v[34:35], v[74:75], v[34:35], v[78:79]
	v_pk_fma_f32 v[32:33], v[62:63], v[32:33], v[70:71]
	v_cvt_pk_bf16_f32 v40, v40, v41
	v_pk_fma_f32 v[42:43], v[60:61], v[44:45], v[68:69]
	v_cvt_pk_bf16_f32 v34, v34, v35
	s_nop 0
	v_cvt_pk_bf16_f32 v35, v42, v43
	v_cvt_pk_bf16_f32 v32, v32, v33
	ds_write_b16 v192, v40 offset:34816
	ds_write_b16_d16_hi v192, v40 offset:35088
	ds_write_b16 v192, v34 offset:35360
	ds_write_b16_d16_hi v192, v34 offset:35632
	ds_write_b16 v192, v35 offset:35904
	ds_write_b16_d16_hi v192, v35 offset:36176
	ds_write_b16 v192, v32 offset:36448
	ds_write_b16_d16_hi v192, v32 offset:36720
.LBB0_713:
	s_waitcnt lgkmcnt(0)
	s_barrier
	global_load_dwordx4 v[68:71], v[124:125], off offset:2064
	global_load_dwordx4 v[80:83], v[124:125], off offset:2048
	global_load_dwordx4 v[76:79], v[126:127], off offset:2064
	global_load_dwordx4 v[84:87], v[126:127], off offset:2048
	v_add_co_u32_e32 v32, vcc, 0x20000, v148
	s_waitcnt vmcnt(9)
	v_mov_b64_e32 v[62:63], v[54:55]
	v_addc_co_u32_e32 v33, vcc, 0, v149, vcc
	global_load_dwordx4 v[72:75], v[32:33], off
	global_load_dwordx4 v[56:59], v[32:33], off offset:64
	s_and_b64 vcc, exec, s[4:5]
	v_mov_b64_e32 v[60:61], v[52:53]
	s_cbranch_vccnz .LBB0_719
	v_add_co_u32_e32 v32, vcc, 0x20000, v148
	s_nop 1
	v_addc_co_u32_e32 v33, vcc, 0, v149, vcc
	global_load_dwordx4 v[60:63], v[32:33], off offset:128

; #define LAS __attribute__((address_space(3)))
; __global__ void __launch_bounds__(NTHR, 2) fwd_megakernel(Args args) {
;     ...
;                 f32x4 a0 = (f32x4){0.f, 0.f, 0.f, 0.f}, a1 = a0;
; #pragma unroll
;                 for (int ks = 0; ks < 4; ++ks) if (ks < nk) {
;                     const int r0 = 16 * (2 * nq) + fr, r1 = r0 + 16, q = ks * 4 + fq;
;                     const bf16x8 x0 = *(const LAS bf16x8*)(Bc + r0 * LDB + ((q ^ ((r0 >> 3) & 15)) * 8)), x1 = *(const LAS bf16x8*)(Bc + r1 * LDB + ((q ^ ((r1 >> 3) & 15)) * 8));
;                     a0 = __builtin_amdgcn_mfma_f32_16x16x32_bf16(x0, cw[ks], a0, 0, 0, 0); a1 = __builtin_amdgcn_mfma_f32_16x16x32_bf16(x1, cw[ks], a1, 0, 0, 0);
;                 }
.LBB0_721:
	ds_read_b128 v[40:43], v193 offset:34816
	ds_read_b128 v[44:47], v194 offset:34816
	global_load_dword v168, v[160:161], off offset:2048
	s_and_b64 vcc, exec, s[4:5]
	s_waitcnt lgkmcnt(1)
	v_mfma_f32_16x16x32_bf16 v[40:43], v[40:43], v[64:67], 0
	ds_read_b128 v[96:99], v196 offset:34816
	s_waitcnt lgkmcnt(1)
	v_mfma_f32_16x16x32_bf16 v[64:67], v[44:47], v[64:67], 0
	ds_read_b128 v[44:47], v195 offset:34816
	global_load_dwordx2 v[172:173], v[150:151], off offset:1024
	global_load_dwordx2 v[170:171], v[150:151], off offset:1056
	s_mov_b64 s[100:101], vcc
	v_lshl_add_u64 v[226:227], v[112:113], 0, s[24:25]
	global_load_dwordx4 v[222:225], v[112:113], off offset:1280
	global_load_dwordx4 v[226:229], v[226:227], off offset:1280
	s_mov_b64 vcc, s[4:5]
	s_cbranch_vccnz .Lgpv_g5
	v_lshlrev_b64 v[230:231], 11, v[152:153]
	v_lshl_add_u64 v[230:231], v[122:123], 0, v[230:231]
	v_lshl_add_u64 v[234:235], v[230:231], 0, s[24:25]
	global_load_dwordx4 v[230:233], v[230:231], off offset:1280
	global_load_dwordx4 v[234:237], v[234:235], off offset:1280
.Lgpv_g5:
	s_mov_b64 vcc, s[100:101]
	s_waitcnt lgkmcnt(0)
	v_mfma_f32_16x16x32_bf16 v[44:47], v[44:47], v[48:51], v[40:43]
	v_mfma_f32_16x16x32_bf16 v[40:43], v[96:99], v[48:51], v[64:67]
	s_cbranch_vccnz .LBB0_723
	ds_read_b128 v[48:51], v197 offset:34816
	s_nop 0
	ds_read_b128 v[64:67], v198 offset:34816
	s_waitcnt lgkmcnt(1)
	v_mfma_f32_16x16x32_bf16 v[44:47], v[48:51], v[52:55], v[44:47]
	s_waitcnt lgkmcnt(0)
	v_mfma_f32_16x16x32_bf16 v[40:43], v[64:67], v[52:55], v[40:43]

; #define LAS __attribute__((address_space(3)))
; __device__ __forceinline__ unsigned cvt_pk_bf16(float lo, float hi) { unsigned r; asm volatile("v_cvt_pk_bf16_f32 %0, %1, %2" : "=v"(r) : "v"(lo), "v"(hi)); return r; }
; __device__ __forceinline__ float bf_lo(unsigned u) { return __uint_as_float(u << 16); }
; __device__ __forceinline__ float bf_hi(unsigned u) { return __uint_as_float(u & 0xffff0000u); }
; __global__ void __launch_bounds__(NTHR, 2) fwd_megakernel(Args args) {
;     ...
;                 for (int k = 0; k < 4; ++k) if (k < nk) { const int j = jb + 32 * k; const u32x4 v = pv[k]; const f32x2 ms = st[j];
;                     const f32x4 x0 = (f32x4){bf_lo(v.x), bf_hi(v.x), bf_lo(v.y), bf_hi(v.y)}, x1 = (f32x4){bf_lo(v.z), bf_hi(v.z), bf_lo(v.w), bf_hi(v.w)};
;                     const f32x4 y0 = (x0 - ms.x) * ms.y * pg0 + pb0, y1 = (x1 - ms.x) * ms.y * pg1 + pb1;
;                     LAS bf16_t* d = Bc + (c8 * 8) * LDB + (j ^ (8 * c8));
;                     const unsigned p0 = cvt_pk_bf16(y0[0], y0[1]), p1 = cvt_pk_bf16(y0[2], y0[3]), p2 = cvt_pk_bf16(y1[0], y1[1]), p3 = cvt_pk_bf16(y1[2], y1[3]);
;                     d[0 * LDB] = (bf16_t)(p0 & 0xffffu); d[1 * LDB] = (bf16_t)(p0 >> 16); d[2 * LDB] = (bf16_t)(p1 & 0xffffu); d[3 * LDB] = (bf16_t)(p1 >> 16);
;                     d[4 * LDB] = (bf16_t)(p2 & 0xffffu); d[5 * LDB] = (bf16_t)(p2 >> 16); d[6 * LDB] = (bf16_t)(p3 & 0xffffu); d[7 * LDB] = (bf16_t)(p3 >> 16); }
;                 bf16x8 cw[4];
; #pragma unroll
;                 for (int ks = 0; ks < 4; ++ks) cw[ks] = pw[ks];
;                 const u32x2 u0 = pu0, u1 = pu1; const float bs = pbs;
;                 __syncthreads();
;                 if (h + 1 < 8) SGU_PREFETCH(h + 1);
.LBB0_725:
	ds_read_b64 v[36:37], v181
	s_waitcnt vmcnt(12)
	v_lshlrev_b32_e32 v48, 16, v238
	v_and_b32_e32 v49, 0xffff0000, v238
	v_lshlrev_b32_e32 v38, 16, v239
	v_and_b32_e32 v39, 0xffff0000, v239
	v_lshlrev_b32_e32 v52, 16, v240
	v_and_b32_e32 v53, 0xffff0000, v240
	v_lshlrev_b32_e32 v50, 16, v241
	v_and_b32_e32 v51, 0xffff0000, v241
	s_waitcnt lgkmcnt(0)
	v_sub_f32_e32 v49, v49, v36
	v_sub_f32_e32 v48, v48, v36
	v_sub_f32_e32 v39, v39, v36
	v_sub_f32_e32 v38, v38, v36
	v_pk_mul_f32 v[48:49], v[36:37], v[48:49] op_sel:[1,0]
	v_sub_f32_e32 v51, v51, v36
	v_sub_f32_e32 v50, v50, v36
	v_sub_f32_e32 v53, v53, v36
	v_sub_f32_e32 v52, v52, v36
	v_pk_mul_f32 v[38:39], v[36:37], v[38:39] op_sel:[1,0]
	s_waitcnt vmcnt(7)
	v_pk_fma_f32 v[48:49], v[80:81], v[48:49], v[84:85]
	v_pk_mul_f32 v[52:53], v[36:37], v[52:53] op_sel:[1,0]
	v_pk_mul_f32 v[36:37], v[36:37], v[50:51] op_sel:[1,0]
	v_pk_fma_f32 v[38:39], v[82:83], v[38:39], v[86:87]
	v_pk_fma_f32 v[36:37], v[70:71], v[36:37], v[78:79]
	v_cvt_pk_bf16_f32 v48, v48, v49
	v_pk_fma_f32 v[50:51], v[68:69], v[52:53], v[76:77]
	v_cvt_pk_bf16_f32 v38, v38, v39
	v_and_b32_e32 v49, 0xffff0000, v242
	v_cvt_pk_bf16_f32 v39, v50, v51
	v_cvt_pk_bf16_f32 v36, v36, v37
	ds_write_b16 v186, v48
	ds_write_b16_d16_hi v186, v48 offset:272
	ds_write_b16 v186, v38 offset:544
	ds_write_b16_d16_hi v186, v38 offset:816
	ds_write_b16 v186, v39 offset:1088
	ds_write_b16_d16_hi v186, v39 offset:1360
	ds_write_b16 v186, v36 offset:1632
	ds_write_b16_d16_hi v186, v36 offset:1904
	ds_read_b64 v[36:37], v187
	v_lshlrev_b32_e32 v48, 16, v242
	v_lshlrev_b32_e32 v38, 16, v243
	v_and_b32_e32 v39, 0xffff0000, v243
	v_lshlrev_b32_e32 v52, 16, v244
	v_and_b32_e32 v53, 0xffff0000, v244
	v_lshlrev_b32_e32 v50, 16, v245
	v_and_b32_e32 v51, 0xffff0000, v245
	s_waitcnt lgkmcnt(0)
	v_sub_f32_e32 v49, v49, v36
	v_sub_f32_e32 v48, v48, v36
	v_sub_f32_e32 v39, v39, v36
	v_sub_f32_e32 v38, v38, v36
	v_pk_mul_f32 v[48:49], v[36:37], v[48:49] op_sel:[1,0]
	v_sub_f32_e32 v51, v51, v36
	v_sub_f32_e32 v50, v50, v36
	v_sub_f32_e32 v53, v53, v36
	v_sub_f32_e32 v52, v52, v36
	v_pk_mul_f32 v[38:39], v[36:37], v[38:39] op_sel:[1,0]
	v_pk_fma_f32 v[48:49], v[80:81], v[48:49], v[84:85]
	v_pk_mul_f32 v[52:53], v[36:37], v[52:53] op_sel:[1,0]
	v_pk_mul_f32 v[36:37], v[36:37], v[50:51] op_sel:[1,0]
	v_pk_fma_f32 v[38:39], v[82:83], v[38:39], v[86:87]
	v_pk_fma_f32 v[36:37], v[70:71], v[36:37], v[78:79]
	v_cvt_pk_bf16_f32 v48, v48, v49
	s_and_b64 vcc, exec, s[4:5]
	v_pk_fma_f32 v[50:51], v[68:69], v[52:53], v[76:77]
	v_cvt_pk_bf16_f32 v38, v38, v39
	s_nop 0
	v_cvt_pk_bf16_f32 v39, v50, v51
	v_cvt_pk_bf16_f32 v36, v36, v37
	ds_write_b16 v188, v48
	ds_write_b16_d16_hi v188, v48 offset:272
	ds_write_b16 v188, v38 offset:544
	ds_write_b16_d16_hi v188, v38 offset:816
	ds_write_b16 v188, v39 offset:1088
	ds_write_b16_d16_hi v188, v39 offset:1360
	ds_write_b16 v188, v36 offset:1632
	ds_write_b16_d16_hi v188, v36 offset:1904
	s_cbranch_vccnz .LBB0_727
	ds_read_b64 v[36:37], v189
	v_lshlrev_b32_e32 v48, 16, v246
	v_and_b32_e32 v49, 0xffff0000, v246
	v_lshlrev_b32_e32 v38, 16, v247
	v_and_b32_e32 v39, 0xffff0000, v247
	v_lshlrev_b32_e32 v52, 16, v248
	v_and_b32_e32 v53, 0xffff0000, v248
	v_lshlrev_b32_e32 v50, 16, v249
	v_and_b32_e32 v51, 0xffff0000, v249
	s_waitcnt lgkmcnt(0)
	v_sub_f32_e32 v49, v49, v36
	v_sub_f32_e32 v48, v48, v36
	v_sub_f32_e32 v39, v39, v36
	v_sub_f32_e32 v38, v38, v36
	v_pk_mul_f32 v[48:49], v[36:37], v[48:49] op_sel:[1,0]
	v_sub_f32_e32 v51, v51, v36
	v_sub_f32_e32 v50, v50, v36
	v_sub_f32_e32 v53, v53, v36
	v_sub_f32_e32 v52, v52, v36
	v_pk_mul_f32 v[38:39], v[36:37], v[38:39] op_sel:[1,0]
	v_pk_fma_f32 v[48:49], v[80:81], v[48:49], v[84:85]
	v_pk_mul_f32 v[52:53], v[36:37], v[52:53] op_sel:[1,0]
	v_pk_mul_f32 v[36:37], v[36:37], v[50:51] op_sel:[1,0]
	v_pk_fma_f32 v[38:39], v[82:83], v[38:39], v[86:87]
	v_pk_fma_f32 v[36:37], v[70:71], v[36:37], v[78:79]
	v_cvt_pk_bf16_f32 v48, v48, v49
	v_pk_fma_f32 v[50:51], v[68:69], v[52:53], v[76:77]
	v_cvt_pk_bf16_f32 v38, v38, v39
	v_and_b32_e32 v49, 0xffff0000, v250
	v_cvt_pk_bf16_f32 v39, v50, v51
	v_cvt_pk_bf16_f32 v36, v36, v37
	ds_write_b16 v190, v48
	ds_write_b16_d16_hi v190, v48 offset:272
	ds_write_b16 v190, v38 offset:544
	ds_write_b16_d16_hi v190, v38 offset:816
	ds_write_b16 v190, v39 offset:1088
	ds_write_b16_d16_hi v190, v39 offset:1360
	ds_write_b16 v190, v36 offset:1632
	ds_write_b16_d16_hi v190, v36 offset:1904
	ds_read_b64 v[36:37], v191
	v_lshlrev_b32_e32 v48, 16, v250
	v_lshlrev_b32_e32 v38, 16, v251
	v_and_b32_e32 v39, 0xffff0000, v251
	v_lshlrev_b32_e32 v52, 16, v252
	v_and_b32_e32 v53, 0xffff0000, v252
	v_lshlrev_b32_e32 v50, 16, v253
	v_and_b32_e32 v51, 0xffff0000, v253
	s_waitcnt lgkmcnt(0)
	v_sub_f32_e32 v49, v49, v36
	v_sub_f32_e32 v48, v48, v36
	v_sub_f32_e32 v39, v39, v36
	v_sub_f32_e32 v38, v38, v36
	v_pk_mul_f32 v[48:49], v[36:37], v[48:49] op_sel:[1,0]
	v_sub_f32_e32 v51, v51, v36
	v_sub_f32_e32 v50, v50, v36
	v_sub_f32_e32 v53, v53, v36
	v_sub_f32_e32 v52, v52, v36
	v_pk_mul_f32 v[38:39], v[36:37], v[38:39] op_sel:[1,0]
	v_pk_fma_f32 v[48:49], v[80:81], v[48:49], v[84:85]
	v_pk_mul_f32 v[52:53], v[36:37], v[52:53] op_sel:[1,0]
	v_pk_mul_f32 v[36:37], v[36:37], v[50:51] op_sel:[1,0]
	v_pk_fma_f32 v[38:39], v[82:83], v[38:39], v[86:87]
	v_pk_fma_f32 v[36:37], v[70:71], v[36:37], v[78:79]
	v_cvt_pk_bf16_f32 v48, v48, v49
	v_pk_fma_f32 v[50:51], v[68:69], v[52:53], v[76:77]
	v_cvt_pk_bf16_f32 v38, v38, v39
	s_nop 0
	v_cvt_pk_bf16_f32 v39, v50, v51
	v_cvt_pk_bf16_f32 v36, v36, v37
	ds_write_b16 v192, v48
	ds_write_b16_d16_hi v192, v48 offset:272
	ds_write_b16 v192, v38 offset:544
	ds_write_b16_d16_hi v192, v38 offset:816
	ds_write_b16 v192, v39 offset:1088
	ds_write_b16_d16_hi v192, v39 offset:1360
	ds_write_b16 v192, v36 offset:1632
	ds_write_b16_d16_hi v192, v36 offset:1904
.LBB0_727:
	s_waitcnt lgkmcnt(0)
	s_barrier
	global_load_dwordx4 v[76:79], v[124:125], off offset:2576
	global_load_dwordx4 v[88:91], v[124:125], off offset:2560
	global_load_dwordx4 v[80:83], v[126:127], off offset:2576
	global_load_dwordx4 v[92:95], v[126:127], off offset:2560
	v_add_co_u32_e32 v36, vcc, 0x28000, v148
	s_waitcnt vmcnt(9)
	v_mov_b64_e32 v[70:71], v[62:63]
	v_addc_co_u32_e32 v37, vcc, 0, v149, vcc
	global_load_dwordx4 v[84:87], v[36:37], off
	global_load_dwordx4 v[64:67], v[36:37], off offset:64
	s_and_b64 vcc, exec, s[4:5]
	v_mov_b64_e32 v[68:69], v[60:61]
	s_cbranch_vccnz .LBB0_733
	v_add_co_u32_e32 v36, vcc, 0x28000, v148
	s_nop 1
	v_addc_co_u32_e32 v37, vcc, 0, v149, vcc
	global_load_dwordx4 v[68:71], v[36:37], off offset:128

; #define LAS __attribute__((address_space(3)))
; __global__ void __launch_bounds__(NTHR, 2) fwd_megakernel(Args args) {
;     ...
;                 f32x4 a0 = (f32x4){0.f, 0.f, 0.f, 0.f}, a1 = a0;
; #pragma unroll
;                 for (int ks = 0; ks < 4; ++ks) if (ks < nk) {
;                     const int r0 = 16 * (2 * nq) + fr, r1 = r0 + 16, q = ks * 4 + fq;
;                     const bf16x8 x0 = *(const LAS bf16x8*)(Bc + r0 * LDB + ((q ^ ((r0 >> 3) & 15)) * 8)), x1 = *(const LAS bf16x8*)(Bc + r1 * LDB + ((q ^ ((r1 >> 3) & 15)) * 8));
;                     a0 = __builtin_amdgcn_mfma_f32_16x16x32_bf16(x0, cw[ks], a0, 0, 0, 0); a1 = __builtin_amdgcn_mfma_f32_16x16x32_bf16(x1, cw[ks], a1, 0, 0, 0);
;                 }
.LBB0_735:
	ds_read_b128 v[48:51], v193
	ds_read_b128 v[52:55], v194
	global_load_dword v174, v[160:161], off offset:2560
	s_and_b64 vcc, exec, s[4:5]
	s_waitcnt lgkmcnt(1)
	v_mfma_f32_16x16x32_bf16 v[48:51], v[48:51], v[72:75], 0
	ds_read_b128 v[104:107], v196
	s_waitcnt lgkmcnt(1)
	v_mfma_f32_16x16x32_bf16 v[72:75], v[52:55], v[72:75], 0
	ds_read_b128 v[52:55], v195
	global_load_dwordx2 v[178:179], v[150:151], off offset:1280
	global_load_dwordx2 v[176:177], v[150:151], off offset:1312
	s_mov_b64 s[100:101], vcc
	v_lshl_add_u64 v[242:243], v[112:113], 0, s[24:25]
	global_load_dwordx4 v[238:241], v[112:113], off offset:1536
	global_load_dwordx4 v[242:245], v[242:243], off offset:1536
	s_mov_b64 vcc, s[4:5]
	s_cbranch_vccnz .Lgpv_g6
	v_lshlrev_b64 v[246:247], 11, v[152:153]
	v_lshl_add_u64 v[246:247], v[122:123], 0, v[246:247]
	v_lshl_add_u64 v[250:251], v[246:247], 0, s[24:25]
	global_load_dwordx4 v[246:249], v[246:247], off offset:1536
	global_load_dwordx4 v[250:253], v[250:251], off offset:1536
.Lgpv_g6:
	s_mov_b64 vcc, s[100:101]
	s_waitcnt lgkmcnt(0)
	v_mfma_f32_16x16x32_bf16 v[52:55], v[52:55], v[56:59], v[48:51]
	v_mfma_f32_16x16x32_bf16 v[48:51], v[104:107], v[56:59], v[72:75]
	s_cbranch_vccnz .LBB0_737
	ds_read_b128 v[56:59], v197
	s_nop 0
	ds_read_b128 v[72:75], v198
	s_waitcnt lgkmcnt(1)
	v_mfma_f32_16x16x32_bf16 v[52:55], v[56:59], v[60:63], v[52:55]
	s_waitcnt lgkmcnt(0)
	v_mfma_f32_16x16x32_bf16 v[48:51], v[72:75], v[60:63], v[48:51]

; #define LAS __attribute__((address_space(3)))
; __device__ __forceinline__ unsigned cvt_pk_bf16(float lo, float hi) { unsigned r; asm volatile("v_cvt_pk_bf16_f32 %0, %1, %2" : "=v"(r) : "v"(lo), "v"(hi)); return r; }
; __device__ __forceinline__ float bf_lo(unsigned u) { return __uint_as_float(u << 16); }
; __device__ __forceinline__ float bf_hi(unsigned u) { return __uint_as_float(u & 0xffff0000u); }
; __global__ void __launch_bounds__(NTHR, 2) fwd_megakernel(Args args) {
;     ...
;                 for (int k = 0; k < 4; ++k) if (k < nk) { const int j = jb + 32 * k; const u32x4 v = pv[k]; const f32x2 ms = st[j];
;                     const f32x4 x0 = (f32x4){bf_lo(v.x), bf_hi(v.x), bf_lo(v.y), bf_hi(v.y)}, x1 = (f32x4){bf_lo(v.z), bf_hi(v.z), bf_lo(v.w), bf_hi(v.w)};
;                     const f32x4 y0 = (x0 - ms.x) * ms.y * pg0 + pb0, y1 = (x1 - ms.x) * ms.y * pg1 + pb1;
;                     LAS bf16_t* d = Bc + (c8 * 8) * LDB + (j ^ (8 * c8));
;                     const unsigned p0 = cvt_pk_bf16(y0[0], y0[1]), p1 = cvt_pk_bf16(y0[2], y0[3]), p2 = cvt_pk_bf16(y1[0], y1[1]), p3 = cvt_pk_bf16(y1[2], y1[3]);
;                     d[0 * LDB] = (bf16_t)(p0 & 0xffffu); d[1 * LDB] = (bf16_t)(p0 >> 16); d[2 * LDB] = (bf16_t)(p1 & 0xffffu); d[3 * LDB] = (bf16_t)(p1 >> 16);
;                     d[4 * LDB] = (bf16_t)(p2 & 0xffffu); d[5 * LDB] = (bf16_t)(p2 >> 16); d[6 * LDB] = (bf16_t)(p3 & 0xffffu); d[7 * LDB] = (bf16_t)(p3 >> 16); }
;                 bf16x8 cw[4];
; #pragma unroll
;                 for (int ks = 0; ks < 4; ++ks) cw[ks] = pw[ks];
;                 const u32x2 u0 = pu0, u1 = pu1; const float bs = pbs;
;                 __syncthreads();
;                 if (h + 1 < 8) SGU_PREFETCH(h + 1);
.LBB0_739:
	ds_read_b64 v[32:33], v181
	s_waitcnt vmcnt(12)
	v_lshlrev_b32_e32 v56, 16, v222
	v_and_b32_e32 v57, 0xffff0000, v222
	v_lshlrev_b32_e32 v34, 16, v223
	v_and_b32_e32 v35, 0xffff0000, v223
	v_lshlrev_b32_e32 v60, 16, v224
	v_and_b32_e32 v61, 0xffff0000, v224
	v_lshlrev_b32_e32 v58, 16, v225
	v_and_b32_e32 v59, 0xffff0000, v225
	s_waitcnt lgkmcnt(0)
	v_sub_f32_e32 v57, v57, v32
	v_sub_f32_e32 v56, v56, v32
	v_sub_f32_e32 v35, v35, v32
	v_sub_f32_e32 v34, v34, v32
	v_pk_mul_f32 v[56:57], v[32:33], v[56:57] op_sel:[1,0]
	v_sub_f32_e32 v59, v59, v32
	v_sub_f32_e32 v58, v58, v32
	v_sub_f32_e32 v61, v61, v32
	v_sub_f32_e32 v60, v60, v32
	v_pk_mul_f32 v[34:35], v[32:33], v[34:35] op_sel:[1,0]
	s_waitcnt vmcnt(7)
	v_pk_fma_f32 v[56:57], v[88:89], v[56:57], v[92:93]
	v_pk_mul_f32 v[60:61], v[32:33], v[60:61] op_sel:[1,0]
	v_pk_mul_f32 v[32:33], v[32:33], v[58:59] op_sel:[1,0]
	v_pk_fma_f32 v[34:35], v[90:91], v[34:35], v[94:95]
	v_pk_fma_f32 v[32:33], v[78:79], v[32:33], v[82:83]
	v_cvt_pk_bf16_f32 v56, v56, v57
	v_pk_fma_f32 v[58:59], v[76:77], v[60:61], v[80:81]
	v_cvt_pk_bf16_f32 v34, v34, v35
	v_and_b32_e32 v57, 0xffff0000, v226
	v_cvt_pk_bf16_f32 v35, v58, v59
	v_cvt_pk_bf16_f32 v32, v32, v33
	ds_write_b16 v186, v56 offset:34816
	ds_write_b16_d16_hi v186, v56 offset:35088
	ds_write_b16 v186, v34 offset:35360
	ds_write_b16_d16_hi v186, v34 offset:35632
	ds_write_b16 v186, v35 offset:35904
	ds_write_b16_d16_hi v186, v35 offset:36176
	ds_write_b16 v186, v32 offset:36448
	ds_write_b16_d16_hi v186, v32 offset:36720
	ds_read_b64 v[32:33], v187
	v_lshlrev_b32_e32 v56, 16, v226
	v_lshlrev_b32_e32 v34, 16, v227
	v_and_b32_e32 v35, 0xffff0000, v227
	v_lshlrev_b32_e32 v60, 16, v228
	v_and_b32_e32 v61, 0xffff0000, v228
	v_lshlrev_b32_e32 v58, 16, v229
	v_and_b32_e32 v59, 0xffff0000, v229
	s_waitcnt lgkmcnt(0)
	v_sub_f32_e32 v57, v57, v32
	v_sub_f32_e32 v56, v56, v32
	v_sub_f32_e32 v35, v35, v32
	v_sub_f32_e32 v34, v34, v32
	v_pk_mul_f32 v[56:57], v[32:33], v[56:57] op_sel:[1,0]
	v_sub_f32_e32 v59, v59, v32
	v_sub_f32_e32 v58, v58, v32
	v_sub_f32_e32 v61, v61, v32
	v_sub_f32_e32 v60, v60, v32
	v_pk_mul_f32 v[34:35], v[32:33], v[34:35] op_sel:[1,0]
	v_pk_fma_f32 v[56:57], v[88:89], v[56:57], v[92:93]
	v_pk_mul_f32 v[60:61], v[32:33], v[60:61] op_sel:[1,0]
	v_pk_mul_f32 v[32:33], v[32:33], v[58:59] op_sel:[1,0]
	v_pk_fma_f32 v[34:35], v[90:91], v[34:35], v[94:95]
	v_pk_fma_f32 v[32:33], v[78:79], v[32:33], v[82:83]
	v_cvt_pk_bf16_f32 v56, v56, v57
	s_and_b64 vcc, exec, s[4:5]
	v_pk_fma_f32 v[58:59], v[76:77], v[60:61], v[80:81]
	v_cvt_pk_bf16_f32 v34, v34, v35
	s_nop 0
	v_cvt_pk_bf16_f32 v35, v58, v59
	v_cvt_pk_bf16_f32 v32, v32, v33
	ds_write_b16 v188, v56 offset:34816
	ds_write_b16_d16_hi v188, v56 offset:35088
	ds_write_b16 v188, v34 offset:35360
	ds_write_b16_d16_hi v188, v34 offset:35632
	ds_write_b16 v188, v35 offset:35904
	ds_write_b16_d16_hi v188, v35 offset:36176
	ds_write_b16 v188, v32 offset:36448
	ds_write_b16_d16_hi v188, v32 offset:36720
	s_cbranch_vccnz .LBB0_741
	ds_read_b64 v[32:33], v189
	v_lshlrev_b32_e32 v56, 16, v230
	v_and_b32_e32 v57, 0xffff0000, v230
	v_lshlrev_b32_e32 v34, 16, v231
	v_and_b32_e32 v35, 0xffff0000, v231
	v_lshlrev_b32_e32 v60, 16, v232
	v_and_b32_e32 v61, 0xffff0000, v232
	v_lshlrev_b32_e32 v58, 16, v233
	v_and_b32_e32 v59, 0xffff0000, v233
	s_waitcnt lgkmcnt(0)
	v_sub_f32_e32 v57, v57, v32
	v_sub_f32_e32 v56, v56, v32
	v_sub_f32_e32 v35, v35, v32
	v_sub_f32_e32 v34, v34, v32
	v_pk_mul_f32 v[56:57], v[32:33], v[56:57] op_sel:[1,0]
	v_sub_f32_e32 v59, v59, v32
	v_sub_f32_e32 v58, v58, v32
	v_sub_f32_e32 v61, v61, v32
	v_sub_f32_e32 v60, v60, v32
	v_pk_mul_f32 v[34:35], v[32:33], v[34:35] op_sel:[1,0]
	v_pk_fma_f32 v[56:57], v[88:89], v[56:57], v[92:93]
	v_pk_mul_f32 v[60:61], v[32:33], v[60:61] op_sel:[1,0]
	v_pk_mul_f32 v[32:33], v[32:33], v[58:59] op_sel:[1,0]
	v_pk_fma_f32 v[34:35], v[90:91], v[34:35], v[94:95]
	v_pk_fma_f32 v[32:33], v[78:79], v[32:33], v[82:83]
	v_cvt_pk_bf16_f32 v56, v56, v57
	v_pk_fma_f32 v[58:59], v[76:77], v[60:61], v[80:81]
	v_cvt_pk_bf16_f32 v34, v34, v35
	v_and_b32_e32 v57, 0xffff0000, v234
	v_cvt_pk_bf16_f32 v35, v58, v59
	v_cvt_pk_bf16_f32 v32, v32, v33
	ds_write_b16 v190, v56 offset:34816
	ds_write_b16_d16_hi v190, v56 offset:35088
	ds_write_b16 v190, v34 offset:35360
	ds_write_b16_d16_hi v190, v34 offset:35632
	ds_write_b16 v190, v35 offset:35904
	ds_write_b16_d16_hi v190, v35 offset:36176
	ds_write_b16 v190, v32 offset:36448
	ds_write_b16_d16_hi v190, v32 offset:36720
	ds_read_b64 v[32:33], v191
	v_lshlrev_b32_e32 v56, 16, v234
	v_lshlrev_b32_e32 v34, 16, v235
	v_and_b32_e32 v35, 0xffff0000, v235
	v_lshlrev_b32_e32 v60, 16, v236
	v_and_b32_e32 v61, 0xffff0000, v236
	v_lshlrev_b32_e32 v58, 16, v237
	v_and_b32_e32 v59, 0xffff0000, v237
	s_waitcnt lgkmcnt(0)
	v_sub_f32_e32 v57, v57, v32
	v_sub_f32_e32 v56, v56, v32
	v_sub_f32_e32 v35, v35, v32
	v_sub_f32_e32 v34, v34, v32
	v_pk_mul_f32 v[56:57], v[32:33], v[56:57] op_sel:[1,0]
	v_sub_f32_e32 v59, v59, v32
	v_sub_f32_e32 v58, v58, v32
	v_sub_f32_e32 v61, v61, v32
	v_sub_f32_e32 v60, v60, v32
	v_pk_mul_f32 v[34:35], v[32:33], v[34:35] op_sel:[1,0]
	v_pk_fma_f32 v[56:57], v[88:89], v[56:57], v[92:93]
	v_pk_mul_f32 v[60:61], v[32:33], v[60:61] op_sel:[1,0]
	v_pk_mul_f32 v[32:33], v[32:33], v[58:59] op_sel:[1,0]
	v_pk_fma_f32 v[34:35], v[90:91], v[34:35], v[94:95]
	v_pk_fma_f32 v[32:33], v[78:79], v[32:33], v[82:83]
	v_cvt_pk_bf16_f32 v56, v56, v57
	v_pk_fma_f32 v[58:59], v[76:77], v[60:61], v[80:81]
	v_cvt_pk_bf16_f32 v34, v34, v35
	s_nop 0
	v_cvt_pk_bf16_f32 v35, v58, v59
	v_cvt_pk_bf16_f32 v32, v32, v33
	ds_write_b16 v192, v56 offset:34816
	ds_write_b16_d16_hi v192, v56 offset:35088
	ds_write_b16 v192, v34 offset:35360
	ds_write_b16_d16_hi v192, v34 offset:35632
	ds_write_b16 v192, v35 offset:35904
	ds_write_b16_d16_hi v192, v35 offset:36176
	ds_write_b16 v192, v32 offset:36448
	ds_write_b16_d16_hi v192, v32 offset:36720
.LBB0_741:
	s_waitcnt lgkmcnt(0)
	s_barrier
	global_load_dwordx4 v[32:35], v[124:125], off offset:3088
	global_load_dwordx4 v[96:99], v[124:125], off offset:3072
	global_load_dwordx4 v[92:95], v[126:127], off offset:3088
	global_load_dwordx4 v[100:103], v[126:127], off offset:3072
	v_add_co_u32_e32 v56, vcc, 0x30000, v148
	s_waitcnt vmcnt(9)
	v_mov_b64_e32 v[82:83], v[70:71]
	v_addc_co_u32_e32 v57, vcc, 0, v149, vcc
	global_load_dwordx4 v[88:91], v[56:57], off
	global_load_dwordx4 v[76:79], v[56:57], off offset:64
	s_and_b64 vcc, exec, s[4:5]
	v_mov_b64_e32 v[80:81], v[68:69]
	s_cbranch_vccnz .LBB0_747
	v_add_co_u32_e32 v56, vcc, 0x30000, v148
	s_nop 1
	v_addc_co_u32_e32 v57, vcc, 0, v149, vcc
	global_load_dwordx4 v[80:83], v[56:57], off offset:128

; #define LAS __attribute__((address_space(3)))
; __global__ void __launch_bounds__(NTHR, 2) fwd_megakernel(Args args) {
;     ...
;                 f32x4 a0 = (f32x4){0.f, 0.f, 0.f, 0.f}, a1 = a0;
; #pragma unroll
;                 for (int ks = 0; ks < 4; ++ks) if (ks < nk) {
;                     const int r0 = 16 * (2 * nq) + fr, r1 = r0 + 16, q = ks * 4 + fq;
;                     const bf16x8 x0 = *(const LAS bf16x8*)(Bc + r0 * LDB + ((q ^ ((r0 >> 3) & 15)) * 8)), x1 = *(const LAS bf16x8*)(Bc + r1 * LDB + ((q ^ ((r1 >> 3) & 15)) * 8));
;                     a0 = __builtin_amdgcn_mfma_f32_16x16x32_bf16(x0, cw[ks], a0, 0, 0, 0); a1 = __builtin_amdgcn_mfma_f32_16x16x32_bf16(x1, cw[ks], a1, 0, 0, 0);
;                 }
.LBB0_749:
	ds_read_b128 v[56:59], v193 offset:34816
	ds_read_b128 v[60:63], v194 offset:34816
	global_load_dword v180, v[160:161], off offset:3072
	s_and_b64 vcc, exec, s[4:5]
	s_waitcnt lgkmcnt(1)
	v_mfma_f32_16x16x32_bf16 v[56:59], v[56:59], v[84:87], 0
	ds_read_b128 v[116:119], v196 offset:34816
	s_waitcnt lgkmcnt(1)
	v_mfma_f32_16x16x32_bf16 v[84:87], v[60:63], v[84:87], 0
	ds_read_b128 v[60:63], v195 offset:34816
	global_load_dwordx2 v[184:185], v[150:151], off offset:1536
	global_load_dwordx2 v[182:183], v[150:151], off offset:1568
	s_mov_b64 s[100:101], vcc
	v_lshl_add_u64 v[226:227], v[112:113], 0, s[24:25]
	global_load_dwordx4 v[222:225], v[112:113], off offset:1792
	global_load_dwordx4 v[226:229], v[226:227], off offset:1792
	s_mov_b64 vcc, s[4:5]
	s_cbranch_vccnz .Lgpv_g7
	v_lshlrev_b64 v[230:231], 11, v[152:153]
	v_lshl_add_u64 v[230:231], v[122:123], 0, v[230:231]
	v_lshl_add_u64 v[234:235], v[230:231], 0, s[24:25]
	global_load_dwordx4 v[230:233], v[230:231], off offset:1792
	global_load_dwordx4 v[234:237], v[234:235], off offset:1792
.Lgpv_g7:
	s_mov_b64 vcc, s[100:101]
	s_waitcnt lgkmcnt(0)
	v_mfma_f32_16x16x32_bf16 v[60:63], v[60:63], v[64:67], v[56:59]
	v_mfma_f32_16x16x32_bf16 v[56:59], v[116:119], v[64:67], v[84:87]
	s_cbranch_vccnz .LBB0_751
	ds_read_b128 v[64:67], v197 offset:34816
	s_nop 0
	ds_read_b128 v[84:87], v198 offset:34816
	s_waitcnt lgkmcnt(1)
	v_mfma_f32_16x16x32_bf16 v[60:63], v[64:67], v[68:71], v[60:63]
	s_waitcnt lgkmcnt(0)
	v_mfma_f32_16x16x32_bf16 v[56:59], v[84:87], v[68:71], v[56:59]

; #define LAS __attribute__((address_space(3)))
; __device__ __forceinline__ unsigned cvt_pk_bf16(float lo, float hi) { unsigned r; asm volatile("v_cvt_pk_bf16_f32 %0, %1, %2" : "=v"(r) : "v"(lo), "v"(hi)); return r; }
; __device__ __forceinline__ float bf_lo(unsigned u) { return __uint_as_float(u << 16); }
; __device__ __forceinline__ float bf_hi(unsigned u) { return __uint_as_float(u & 0xffff0000u); }
; __global__ void __launch_bounds__(NTHR, 2) fwd_megakernel(Args args) {
;     ...
;                 for (int k = 0; k < 4; ++k) if (k < nk) { const int j = jb + 32 * k; const u32x4 v = pv[k]; const f32x2 ms = st[j];
;                     const f32x4 x0 = (f32x4){bf_lo(v.x), bf_hi(v.x), bf_lo(v.y), bf_hi(v.y)}, x1 = (f32x4){bf_lo(v.z), bf_hi(v.z), bf_lo(v.w), bf_hi(v.w)};
;                     const f32x4 y0 = (x0 - ms.x) * ms.y * pg0 + pb0, y1 = (x1 - ms.x) * ms.y * pg1 + pb1;
;                     LAS bf16_t* d = Bc + (c8 * 8) * LDB + (j ^ (8 * c8));
;                     const unsigned p0 = cvt_pk_bf16(y0[0], y0[1]), p1 = cvt_pk_bf16(y0[2], y0[3]), p2 = cvt_pk_bf16(y1[0], y1[1]), p3 = cvt_pk_bf16(y1[2], y1[3]);
;                     d[0 * LDB] = (bf16_t)(p0 & 0xffffu); d[1 * LDB] = (bf16_t)(p0 >> 16); d[2 * LDB] = (bf16_t)(p1 & 0xffffu); d[3 * LDB] = (bf16_t)(p1 >> 16);
;                     d[4 * LDB] = (bf16_t)(p2 & 0xffffu); d[5 * LDB] = (bf16_t)(p2 >> 16); d[6 * LDB] = (bf16_t)(p3 & 0xffffu); d[7 * LDB] = (bf16_t)(p3 >> 16); }
;                 bf16x8 cw[4];
; #pragma unroll
;                 for (int ks = 0; ks < 4; ++ks) cw[ks] = pw[ks];
;                 const u32x2 u0 = pu0, u1 = pu1; const float bs = pbs;
;                 __syncthreads();
;                 if (h + 1 < 8) SGU_PREFETCH(h + 1);
.LBB0_753:
	ds_read_b64 v[36:37], v181
	s_waitcnt vmcnt(12)
	v_lshlrev_b32_e32 v64, 16, v238
	v_and_b32_e32 v65, 0xffff0000, v238
	v_lshlrev_b32_e32 v38, 16, v239
	v_and_b32_e32 v39, 0xffff0000, v239
	v_lshlrev_b32_e32 v68, 16, v240
	v_and_b32_e32 v69, 0xffff0000, v240
	v_lshlrev_b32_e32 v66, 16, v241
	v_and_b32_e32 v67, 0xffff0000, v241
	s_waitcnt lgkmcnt(0)
	v_sub_f32_e32 v65, v65, v36
	v_sub_f32_e32 v64, v64, v36
	v_sub_f32_e32 v39, v39, v36
	v_sub_f32_e32 v38, v38, v36
	v_pk_mul_f32 v[64:65], v[36:37], v[64:65] op_sel:[1,0]
	v_sub_f32_e32 v67, v67, v36
	v_sub_f32_e32 v66, v66, v36
	v_sub_f32_e32 v69, v69, v36
	v_sub_f32_e32 v68, v68, v36
	v_pk_mul_f32 v[38:39], v[36:37], v[38:39] op_sel:[1,0]
	s_waitcnt vmcnt(7)
	v_pk_fma_f32 v[64:65], v[96:97], v[64:65], v[100:101]
	v_pk_mul_f32 v[68:69], v[36:37], v[68:69] op_sel:[1,0]
	v_pk_mul_f32 v[36:37], v[36:37], v[66:67] op_sel:[1,0]
	v_pk_fma_f32 v[38:39], v[98:99], v[38:39], v[102:103]
	v_pk_fma_f32 v[36:37], v[34:35], v[36:37], v[94:95]
	v_cvt_pk_bf16_f32 v64, v64, v65
	v_pk_fma_f32 v[66:67], v[32:33], v[68:69], v[92:93]
	v_cvt_pk_bf16_f32 v38, v38, v39
	v_and_b32_e32 v65, 0xffff0000, v242
	v_cvt_pk_bf16_f32 v39, v66, v67
	v_cvt_pk_bf16_f32 v36, v36, v37
	ds_write_b16 v186, v64
	ds_write_b16_d16_hi v186, v64 offset:272
	ds_write_b16 v186, v38 offset:544
	ds_write_b16_d16_hi v186, v38 offset:816
	ds_write_b16 v186, v39 offset:1088
	ds_write_b16_d16_hi v186, v39 offset:1360
	ds_write_b16 v186, v36 offset:1632
	ds_write_b16_d16_hi v186, v36 offset:1904
	ds_read_b64 v[36:37], v187
	v_lshlrev_b32_e32 v64, 16, v242
	v_lshlrev_b32_e32 v38, 16, v243
	v_and_b32_e32 v39, 0xffff0000, v243
	v_lshlrev_b32_e32 v68, 16, v244
	v_and_b32_e32 v69, 0xffff0000, v244
	v_lshlrev_b32_e32 v66, 16, v245
	v_and_b32_e32 v67, 0xffff0000, v245
	s_waitcnt lgkmcnt(0)
	v_sub_f32_e32 v65, v65, v36
	v_sub_f32_e32 v64, v64, v36
	v_sub_f32_e32 v39, v39, v36
	v_sub_f32_e32 v38, v38, v36
	v_pk_mul_f32 v[64:65], v[36:37], v[64:65] op_sel:[1,0]
	v_sub_f32_e32 v67, v67, v36
	v_sub_f32_e32 v66, v66, v36
	v_sub_f32_e32 v69, v69, v36
	v_sub_f32_e32 v68, v68, v36
	v_pk_mul_f32 v[38:39], v[36:37], v[38:39] op_sel:[1,0]
	v_pk_fma_f32 v[64:65], v[96:97], v[64:65], v[100:101]
	v_pk_mul_f32 v[68:69], v[36:37], v[68:69] op_sel:[1,0]
	v_pk_mul_f32 v[36:37], v[36:37], v[66:67] op_sel:[1,0]
	v_pk_fma_f32 v[38:39], v[98:99], v[38:39], v[102:103]
	v_pk_fma_f32 v[36:37], v[34:35], v[36:37], v[94:95]
	v_cvt_pk_bf16_f32 v64, v64, v65
	s_and_b64 vcc, exec, s[4:5]
	v_pk_fma_f32 v[66:67], v[32:33], v[68:69], v[92:93]
	v_cvt_pk_bf16_f32 v38, v38, v39
	s_nop 0
	v_cvt_pk_bf16_f32 v39, v66, v67
	v_cvt_pk_bf16_f32 v36, v36, v37
	ds_write_b16 v188, v64
	ds_write_b16_d16_hi v188, v64 offset:272
	ds_write_b16 v188, v38 offset:544
	ds_write_b16_d16_hi v188, v38 offset:816
	ds_write_b16 v188, v39 offset:1088
	ds_write_b16_d16_hi v188, v39 offset:1360
	ds_write_b16 v188, v36 offset:1632
	ds_write_b16_d16_hi v188, v36 offset:1904
	s_cbranch_vccnz .LBB0_755
	ds_read_b64 v[36:37], v189
	v_lshlrev_b32_e32 v64, 16, v246
	v_and_b32_e32 v65, 0xffff0000, v246
	v_lshlrev_b32_e32 v38, 16, v247
	v_and_b32_e32 v39, 0xffff0000, v247
	v_lshlrev_b32_e32 v68, 16, v248
	v_and_b32_e32 v69, 0xffff0000, v248
	v_lshlrev_b32_e32 v66, 16, v249
	v_and_b32_e32 v67, 0xffff0000, v249
	s_waitcnt lgkmcnt(0)
	v_sub_f32_e32 v65, v65, v36
	v_sub_f32_e32 v64, v64, v36
	v_sub_f32_e32 v39, v39, v36
	v_sub_f32_e32 v38, v38, v36
	v_pk_mul_f32 v[64:65], v[36:37], v[64:65] op_sel:[1,0]
	v_sub_f32_e32 v67, v67, v36
	v_sub_f32_e32 v66, v66, v36
	v_sub_f32_e32 v69, v69, v36
	v_sub_f32_e32 v68, v68, v36
	v_pk_mul_f32 v[38:39], v[36:37], v[38:39] op_sel:[1,0]
	v_pk_fma_f32 v[64:65], v[96:97], v[64:65], v[100:101]
	v_pk_mul_f32 v[68:69], v[36:37], v[68:69] op_sel:[1,0]
	v_pk_mul_f32 v[36:37], v[36:37], v[66:67] op_sel:[1,0]
	v_pk_fma_f32 v[38:39], v[98:99], v[38:39], v[102:103]
	v_pk_fma_f32 v[36:37], v[34:35], v[36:37], v[94:95]
	v_cvt_pk_bf16_f32 v64, v64, v65
	v_pk_fma_f32 v[66:67], v[32:33], v[68:69], v[92:93]
	v_cvt_pk_bf16_f32 v38, v38, v39
	v_and_b32_e32 v65, 0xffff0000, v250
	v_cvt_pk_bf16_f32 v39, v66, v67
	v_cvt_pk_bf16_f32 v36, v36, v37
	ds_write_b16 v190, v64
	ds_write_b16_d16_hi v190, v64 offset:272
	ds_write_b16 v190, v38 offset:544
	ds_write_b16_d16_hi v190, v38 offset:816
	ds_write_b16 v190, v39 offset:1088
	ds_write_b16_d16_hi v190, v39 offset:1360
	ds_write_b16 v190, v36 offset:1632
	ds_write_b16_d16_hi v190, v36 offset:1904
	ds_read_b64 v[36:37], v191
	v_lshlrev_b32_e32 v64, 16, v250
	v_lshlrev_b32_e32 v38, 16, v251
	v_and_b32_e32 v39, 0xffff0000, v251
	v_lshlrev_b32_e32 v68, 16, v252
	v_and_b32_e32 v69, 0xffff0000, v252
	v_lshlrev_b32_e32 v66, 16, v253
	v_and_b32_e32 v67, 0xffff0000, v253
	s_waitcnt lgkmcnt(0)
	v_sub_f32_e32 v39, v39, v36
	v_sub_f32_e32 v38, v38, v36
	v_sub_f32_e32 v65, v65, v36
	v_sub_f32_e32 v64, v64, v36
	v_sub_f32_e32 v67, v67, v36
	v_sub_f32_e32 v66, v66, v36
	v_sub_f32_e32 v69, v69, v36
	v_sub_f32_e32 v68, v68, v36
	v_pk_mul_f32 v[64:65], v[36:37], v[64:65] op_sel:[1,0]
	v_pk_mul_f32 v[38:39], v[36:37], v[38:39] op_sel:[1,0]
	v_pk_mul_f32 v[68:69], v[36:37], v[68:69] op_sel:[1,0]
	v_pk_mul_f32 v[36:37], v[36:37], v[66:67] op_sel:[1,0]
	v_pk_fma_f32 v[64:65], v[96:97], v[64:65], v[100:101]
	v_pk_fma_f32 v[34:35], v[34:35], v[36:37], v[94:95]
	v_pk_fma_f32 v[32:33], v[32:33], v[68:69], v[92:93]
	v_cvt_pk_bf16_f32 v36, v64, v65
	v_pk_fma_f32 v[38:39], v[98:99], v[38:39], v[102:103]
	s_nop 0
	v_cvt_pk_bf16_f32 v37, v38, v39
	v_cvt_pk_bf16_f32 v32, v32, v33
	v_cvt_pk_bf16_f32 v33, v34, v35
	ds_write_b16 v192, v36
	ds_write_b16_d16_hi v192, v36 offset:272
	ds_write_b16 v192, v37 offset:544
	ds_write_b16_d16_hi v192, v37 offset:816
	ds_write_b16 v192, v32 offset:1088
	ds_write_b16_d16_hi v192, v32 offset:1360
	ds_write_b16 v192, v33 offset:1632
	ds_write_b16_d16_hi v192, v33 offset:1904
.LBB0_755:
	s_waitcnt lgkmcnt(0)
	s_barrier
	global_load_dwordx4 v[96:99], v[124:125], off offset:3600
	global_load_dwordx4 v[104:107], v[124:125], off offset:3584
	global_load_dwordx4 v[100:103], v[126:127], off offset:3600
	global_load_dwordx4 v[108:111], v[126:127], off offset:3584
	v_add_co_u32_e32 v32, vcc, 0x38000, v148
	s_waitcnt vmcnt(9)
	v_mov_b64_e32 v[36:37], v[80:81]
	v_addc_co_u32_e32 v33, vcc, 0, v149, vcc
	global_load_dwordx4 v[92:95], v[32:33], off
	global_load_dwordx4 v[84:87], v[32:33], off offset:64
	s_and_b64 vcc, exec, s[4:5]
	v_mov_b64_e32 v[38:39], v[82:83]
	s_cbranch_vccnz .LBB0_761
	v_add_co_u32_e32 v32, vcc, 0x38000, v148
	s_nop 1
	v_addc_co_u32_e32 v33, vcc, 0, v149, vcc
	global_load_dwordx4 v[36:39], v[32:33], off offset:128

; #define LAS __attribute__((address_space(3)))
; __device__ __forceinline__ unsigned cvt_pk_bf16(float lo, float hi) { unsigned r; asm volatile("v_cvt_pk_bf16_f32 %0, %1, %2" : "=v"(r) : "v"(lo), "v"(hi)); return r; }
; __device__ __forceinline__ float bf_lo(unsigned u) { return __uint_as_float(u << 16); }
; __device__ __forceinline__ float bf_hi(unsigned u) { return __uint_as_float(u & 0xffff0000u); }
; __global__ void __launch_bounds__(NTHR, 2) fwd_megakernel(Args args) {
;     ...
;                 for (int k = 0; k < 4; ++k) if (k < nk) { const int j = jb + 32 * k; const u32x4 v = pv[k]; const f32x2 ms = st[j];
;                     const f32x4 x0 = (f32x4){bf_lo(v.x), bf_hi(v.x), bf_lo(v.y), bf_hi(v.y)}, x1 = (f32x4){bf_lo(v.z), bf_hi(v.z), bf_lo(v.w), bf_hi(v.w)};
;                     const f32x4 y0 = (x0 - ms.x) * ms.y * pg0 + pb0, y1 = (x1 - ms.x) * ms.y * pg1 + pb1;
;                     LAS bf16_t* d = Bc + (c8 * 8) * LDB + (j ^ (8 * c8));
;                     const unsigned p0 = cvt_pk_bf16(y0[0], y0[1]), p1 = cvt_pk_bf16(y0[2], y0[3]), p2 = cvt_pk_bf16(y1[0], y1[1]), p3 = cvt_pk_bf16(y1[2], y1[3]);
;                     d[0 * LDB] = (bf16_t)(p0 & 0xffffu); d[1 * LDB] = (bf16_t)(p0 >> 16); d[2 * LDB] = (bf16_t)(p1 & 0xffffu); d[3 * LDB] = (bf16_t)(p1 >> 16);
;                     d[4 * LDB] = (bf16_t)(p2 & 0xffffu); d[5 * LDB] = (bf16_t)(p2 >> 16); d[6 * LDB] = (bf16_t)(p3 & 0xffffu); d[7 * LDB] = (bf16_t)(p3 >> 16); }
.LBB0_767:
	ds_read_b64 v[72:73], v181
	s_waitcnt vmcnt(10)
	v_lshlrev_b32_e32 v76, 16, v222
	v_and_b32_e32 v77, 0xffff0000, v222
	v_lshlrev_b32_e32 v74, 16, v223
	v_and_b32_e32 v75, 0xffff0000, v223
	v_lshlrev_b32_e32 v80, 16, v224
	v_and_b32_e32 v81, 0xffff0000, v224
	v_lshlrev_b32_e32 v78, 16, v225
	v_and_b32_e32 v79, 0xffff0000, v225
	s_waitcnt lgkmcnt(0)
	v_sub_f32_e32 v77, v77, v72
	v_sub_f32_e32 v76, v76, v72
	v_sub_f32_e32 v75, v75, v72
	v_sub_f32_e32 v74, v74, v72
	v_pk_mul_f32 v[76:77], v[72:73], v[76:77] op_sel:[1,0]
	v_sub_f32_e32 v79, v79, v72
	v_sub_f32_e32 v78, v78, v72
	v_sub_f32_e32 v81, v81, v72
	v_sub_f32_e32 v80, v80, v72
	v_pk_mul_f32 v[74:75], v[72:73], v[74:75] op_sel:[1,0]
	s_waitcnt vmcnt(5)
	v_pk_fma_f32 v[76:77], v[104:105], v[76:77], v[108:109]
	v_pk_mul_f32 v[80:81], v[72:73], v[80:81] op_sel:[1,0]
	v_pk_mul_f32 v[72:73], v[72:73], v[78:79] op_sel:[1,0]
	v_pk_fma_f32 v[74:75], v[106:107], v[74:75], v[110:111]
	v_pk_fma_f32 v[72:73], v[98:99], v[72:73], v[102:103]
	v_cvt_pk_bf16_f32 v76, v76, v77
	v_pk_fma_f32 v[78:79], v[96:97], v[80:81], v[100:101]
	v_cvt_pk_bf16_f32 v74, v74, v75
	v_and_b32_e32 v77, 0xffff0000, v226
	v_cvt_pk_bf16_f32 v75, v78, v79
	v_cvt_pk_bf16_f32 v72, v72, v73
	ds_write_b16 v186, v76 offset:34816
	ds_write_b16_d16_hi v186, v76 offset:35088
	ds_write_b16 v186, v74 offset:35360
	ds_write_b16_d16_hi v186, v74 offset:35632
	ds_write_b16 v186, v75 offset:35904
	ds_write_b16_d16_hi v186, v75 offset:36176
	ds_write_b16 v186, v72 offset:36448
	ds_write_b16_d16_hi v186, v72 offset:36720
	ds_read_b64 v[72:73], v187
	v_lshlrev_b32_e32 v76, 16, v226
	v_lshlrev_b32_e32 v74, 16, v227
	v_and_b32_e32 v75, 0xffff0000, v227
	v_lshlrev_b32_e32 v80, 16, v228
	v_and_b32_e32 v81, 0xffff0000, v228
	v_lshlrev_b32_e32 v78, 16, v229
	v_and_b32_e32 v79, 0xffff0000, v229
	s_waitcnt lgkmcnt(0)
	v_sub_f32_e32 v77, v77, v72
	v_sub_f32_e32 v76, v76, v72
	v_sub_f32_e32 v75, v75, v72
	v_sub_f32_e32 v74, v74, v72
	v_pk_mul_f32 v[76:77], v[72:73], v[76:77] op_sel:[1,0]
	v_sub_f32_e32 v79, v79, v72
	v_sub_f32_e32 v78, v78, v72
	v_sub_f32_e32 v81, v81, v72
	v_sub_f32_e32 v80, v80, v72
	v_pk_mul_f32 v[74:75], v[72:73], v[74:75] op_sel:[1,0]
	v_pk_fma_f32 v[76:77], v[104:105], v[76:77], v[108:109]
	v_pk_mul_f32 v[80:81], v[72:73], v[80:81] op_sel:[1,0]
	v_pk_mul_f32 v[72:73], v[72:73], v[78:79] op_sel:[1,0]
	v_pk_fma_f32 v[74:75], v[106:107], v[74:75], v[110:111]
	v_pk_fma_f32 v[72:73], v[98:99], v[72:73], v[102:103]
	v_cvt_pk_bf16_f32 v76, v76, v77
	s_and_b64 vcc, exec, s[4:5]
	v_pk_fma_f32 v[78:79], v[96:97], v[80:81], v[100:101]
	v_cvt_pk_bf16_f32 v74, v74, v75
	s_nop 0
	v_cvt_pk_bf16_f32 v75, v78, v79
	v_cvt_pk_bf16_f32 v72, v72, v73
	ds_write_b16 v188, v76 offset:34816
	ds_write_b16_d16_hi v188, v76 offset:35088
	ds_write_b16 v188, v74 offset:35360
	ds_write_b16_d16_hi v188, v74 offset:35632
	ds_write_b16 v188, v75 offset:35904
	ds_write_b16_d16_hi v188, v75 offset:36176
	ds_write_b16 v188, v72 offset:36448
	ds_write_b16_d16_hi v188, v72 offset:36720
	s_cbranch_vccnz .LBB0_769
	ds_read_b64 v[72:73], v189
	v_lshlrev_b32_e32 v76, 16, v230
	v_and_b32_e32 v77, 0xffff0000, v230
	v_lshlrev_b32_e32 v74, 16, v231
	v_and_b32_e32 v75, 0xffff0000, v231
	v_lshlrev_b32_e32 v80, 16, v232
	v_and_b32_e32 v81, 0xffff0000, v232
	v_lshlrev_b32_e32 v78, 16, v233
	v_and_b32_e32 v79, 0xffff0000, v233
	s_waitcnt lgkmcnt(0)
	v_sub_f32_e32 v77, v77, v72
	v_sub_f32_e32 v76, v76, v72
	v_sub_f32_e32 v75, v75, v72
	v_sub_f32_e32 v74, v74, v72
	v_pk_mul_f32 v[76:77], v[72:73], v[76:77] op_sel:[1,0]
	v_sub_f32_e32 v79, v79, v72
	v_sub_f32_e32 v78, v78, v72
	v_sub_f32_e32 v81, v81, v72
	v_sub_f32_e32 v80, v80, v72
	v_pk_mul_f32 v[74:75], v[72:73], v[74:75] op_sel:[1,0]
	v_pk_fma_f32 v[76:77], v[104:105], v[76:77], v[108:109]
	v_pk_mul_f32 v[80:81], v[72:73], v[80:81] op_sel:[1,0]
	v_pk_mul_f32 v[72:73], v[72:73], v[78:79] op_sel:[1,0]
	v_pk_fma_f32 v[74:75], v[106:107], v[74:75], v[110:111]
	v_pk_fma_f32 v[72:73], v[98:99], v[72:73], v[102:103]
	v_cvt_pk_bf16_f32 v76, v76, v77
	v_pk_fma_f32 v[78:79], v[96:97], v[80:81], v[100:101]
	v_cvt_pk_bf16_f32 v74, v74, v75
	v_and_b32_e32 v77, 0xffff0000, v234
	v_cvt_pk_bf16_f32 v75, v78, v79
	v_cvt_pk_bf16_f32 v72, v72, v73
	ds_write_b16 v190, v76 offset:34816
	ds_write_b16_d16_hi v190, v76 offset:35088
	ds_write_b16 v190, v74 offset:35360
	ds_write_b16_d16_hi v190, v74 offset:35632
	ds_write_b16 v190, v75 offset:35904
	ds_write_b16_d16_hi v190, v75 offset:36176
	ds_write_b16 v190, v72 offset:36448
	ds_write_b16_d16_hi v190, v72 offset:36720
	ds_read_b64 v[72:73], v191
	v_lshlrev_b32_e32 v76, 16, v234
	v_lshlrev_b32_e32 v74, 16, v235
	v_and_b32_e32 v75, 0xffff0000, v235
	v_lshlrev_b32_e32 v80, 16, v236
	v_and_b32_e32 v81, 0xffff0000, v236
	v_lshlrev_b32_e32 v78, 16, v237
	v_and_b32_e32 v79, 0xffff0000, v237
	s_waitcnt lgkmcnt(0)
	v_sub_f32_e32 v77, v77, v72
	v_sub_f32_e32 v76, v76, v72
	v_sub_f32_e32 v75, v75, v72
	v_sub_f32_e32 v74, v74, v72
	v_pk_mul_f32 v[76:77], v[72:73], v[76:77] op_sel:[1,0]
	v_sub_f32_e32 v79, v79, v72
	v_sub_f32_e32 v78, v78, v72
	v_sub_f32_e32 v81, v81, v72
	v_sub_f32_e32 v80, v80, v72
	v_pk_mul_f32 v[74:75], v[72:73], v[74:75] op_sel:[1,0]
	v_pk_fma_f32 v[76:77], v[104:105], v[76:77], v[108:109]
	v_pk_mul_f32 v[80:81], v[72:73], v[80:81] op_sel:[1,0]
	v_pk_mul_f32 v[72:73], v[72:73], v[78:79] op_sel:[1,0]
	v_pk_fma_f32 v[74:75], v[106:107], v[74:75], v[110:111]
	v_pk_fma_f32 v[72:73], v[98:99], v[72:73], v[102:103]
	v_cvt_pk_bf16_f32 v76, v76, v77
	v_pk_fma_f32 v[78:79], v[96:97], v[80:81], v[100:101]
	v_cvt_pk_bf16_f32 v74, v74, v75
	s_nop 0
	v_cvt_pk_bf16_f32 v75, v78, v79
	v_cvt_pk_bf16_f32 v72, v72, v73
	ds_write_b16 v192, v76 offset:34816
	ds_write_b16_d16_hi v192, v76 offset:35088
	ds_write_b16 v192, v74 offset:35360
	ds_write_b16_d16_hi v192, v74 offset:35632
	ds_write_b16 v192, v75 offset:35904
	ds_write_b16_d16_hi v192, v75 offset:36176
	ds_write_b16 v192, v72 offset:36448
	ds_write_b16_d16_hi v192, v72 offset:36720
